# combined: P4 conv taps loaded once behind the K-loop, P1 NRB table loads hoisted, attention loop without per-MFMA setprio, residual row pass with next-row prefetch
# baseline (speedup 1.0000x reference)
.LBB0_24:
	ds_read_b128 v[154:157], v138
	ds_read_b128 v[158:161], v139
	ds_read_b128 v[162:165], v140
	ds_read_b128 v[194:197], v141
	ds_read_b128 v[198:201], v142
	ds_read_b128 v[202:205], v143
	ds_read_b128 v[206:209], v144
	ds_read_b128 v[210:213], v145
	s_add_u32 s14, s96, s88
	s_addc_u32 s15, s97, s89
	s_add_u32 s14, s14, 0x4000900
	s_addc_u32 s15, s15, 0
	s_add_u32 s36, s42, s88
	s_addc_u32 s37, s43, s89
	s_cmpk_eq_i32 s88, 0x700
	s_cselect_b32 s27, s87, s15
	s_cselect_b32 s26, s86, s14
	s_cselect_b32 s15, s85, s37
	s_cselect_b32 s14, s84, s36
	v_lshl_add_u64 v[166:167], v[130:131], 0, s[88:89]
	s_add_i32 m0, s94, 0xc000
	ds_read_b128 v[214:217], v137
	ds_read_b128 v[218:221], v137 offset:1024
	ds_read_b128 v[222:225], v137 offset:2048
	ds_read_b128 v[226:229], v137 offset:3072
	ds_read_b128 v[230:233], v137 offset:4096
	ds_read_b128 v[234:237], v137 offset:5120
	ds_read_b128 v[238:241], v137 offset:6144
	ds_read_b128 v[242:245], v137 offset:7168
	global_load_lds_dwordx4 v[166:167], off
	v_lshl_add_u64 v[166:167], v[132:133], 0, s[88:89]
	s_mov_b32 m0, s48
	s_nop 0
	global_load_lds_dwordx4 v[166:167], off
	s_waitcnt vmcnt(8)
	s_waitcnt lgkmcnt(0)
	s_barrier
	s_setprio 1
	s_waitcnt lgkmcnt(0)
	v_mfma_f32_16x16x32_bf16 v[124:127], v[154:157], v[214:217], v[124:127]
	v_mfma_f32_16x16x32_bf16 v[120:123], v[162:165], v[214:217], v[120:123]
	v_mfma_f32_16x16x32_bf16 v[116:119], v[154:157], v[222:225], v[116:119]
	v_mfma_f32_16x16x32_bf16 v[112:115], v[162:165], v[222:225], v[112:115]
	v_mfma_f32_16x16x32_bf16 v[108:111], v[154:157], v[230:233], v[108:111]
	v_mfma_f32_16x16x32_bf16 v[104:107], v[162:165], v[230:233], v[104:107]
	v_mfma_f32_16x16x32_bf16 v[76:79], v[154:157], v[238:241], v[76:79]
	v_mfma_f32_16x16x32_bf16 v[72:75], v[162:165], v[238:241], v[72:75]
	v_mfma_f32_16x16x32_bf16 v[124:127], v[158:161], v[218:221], v[124:127]
	v_mfma_f32_16x16x32_bf16 v[120:123], v[194:197], v[218:221], v[120:123]
	v_mfma_f32_16x16x32_bf16 v[116:119], v[158:161], v[226:229], v[116:119]
	v_mfma_f32_16x16x32_bf16 v[112:115], v[194:197], v[226:229], v[112:115]
	v_mfma_f32_16x16x32_bf16 v[108:111], v[158:161], v[234:237], v[108:111]
	v_mfma_f32_16x16x32_bf16 v[104:107], v[194:197], v[234:237], v[104:107]
	v_mfma_f32_16x16x32_bf16 v[76:79], v[158:161], v[242:245], v[76:79]
	v_mfma_f32_16x16x32_bf16 v[72:75], v[194:197], v[242:245], v[72:75]
	s_setprio 0
	s_setprio 1
	v_mfma_f32_16x16x32_bf16 v[100:103], v[198:201], v[214:217], v[100:103]
	v_mfma_f32_16x16x32_bf16 v[96:99], v[206:209], v[214:217], v[96:99]
	v_mfma_f32_16x16x32_bf16 v[92:95], v[198:201], v[222:225], v[92:95]
	v_mfma_f32_16x16x32_bf16 v[88:91], v[206:209], v[222:225], v[88:91]
	v_mfma_f32_16x16x32_bf16 v[84:87], v[198:201], v[230:233], v[84:87]
	v_mfma_f32_16x16x32_bf16 v[80:83], v[206:209], v[230:233], v[80:83]
	v_mfma_f32_16x16x32_bf16 v[52:55], v[198:201], v[238:241], v[52:55]
	v_mfma_f32_16x16x32_bf16 v[44:47], v[206:209], v[238:241], v[44:47]
	v_mfma_f32_16x16x32_bf16 v[100:103], v[202:205], v[218:221], v[100:103]
	v_mfma_f32_16x16x32_bf16 v[96:99], v[210:213], v[218:221], v[96:99]
	v_mfma_f32_16x16x32_bf16 v[92:95], v[202:205], v[226:229], v[92:95]
	v_mfma_f32_16x16x32_bf16 v[88:91], v[210:213], v[226:229], v[88:91]
	v_mfma_f32_16x16x32_bf16 v[84:87], v[202:205], v[234:237], v[84:87]
	v_mfma_f32_16x16x32_bf16 v[80:83], v[210:213], v[234:237], v[80:83]
	v_mfma_f32_16x16x32_bf16 v[52:55], v[202:205], v[242:245], v[52:55]
	v_mfma_f32_16x16x32_bf16 v[44:47], v[210:213], v[242:245], v[44:47]
	s_setprio 0
	s_barrier
	s_mov_b32 m0, s41
	v_lshl_add_u64 v[166:167], s[14:15], 0, v[168:169]
	s_add_u32 s36, s14, 0x40000
	ds_read_b128 v[214:217], v137 offset:16384
	ds_read_b128 v[218:221], v137 offset:17408
	ds_read_b128 v[222:225], v137 offset:18432
	ds_read_b128 v[226:229], v137 offset:19456
	ds_read_b128 v[230:233], v137 offset:20480
	ds_read_b128 v[234:237], v137 offset:21504
	ds_read_b128 v[238:241], v137 offset:22528
	ds_read_b128 v[242:245], v137 offset:23552
	global_load_lds_dwordx4 v[166:167], off
	v_lshl_add_u64 v[246:247], s[14:15], 0, v[128:129]
	s_mov_b32 m0, s59
	s_addc_u32 s37, s15, 0
	global_load_lds_dwordx4 v[246:247], off
	v_lshl_add_u64 v[248:249], s[36:37], 0, v[168:169]
	s_mov_b32 m0, s95
	v_lshl_add_u64 v[250:251], s[26:27], 0, v[128:129]
	global_load_lds_dwordx4 v[248:249], off
	v_lshl_add_u64 v[248:249], s[36:37], 0, v[128:129]
	s_mov_b32 m0, vcc_lo
	s_nop 0
	global_load_lds_dwordx4 v[248:249], off
	v_lshl_add_u64 v[248:249], s[26:27], 0, v[168:169]
	s_mov_b32 m0, s94
	s_nop 0
	global_load_lds_dwordx4 v[248:249], off
	s_mov_b32 m0, vcc_hi
	s_nop 0
	global_load_lds_dwordx4 v[250:251], off
	s_waitcnt vmcnt(8)
	s_waitcnt lgkmcnt(0)
	s_barrier
	s_setprio 1
	s_waitcnt lgkmcnt(0)
	v_mfma_f32_16x16x32_bf16 v[68:71], v[154:157], v[214:217], v[68:71]
	v_mfma_f32_16x16x32_bf16 v[64:67], v[162:165], v[214:217], v[64:67]
	v_mfma_f32_16x16x32_bf16 v[60:63], v[154:157], v[222:225], v[60:63]
	v_mfma_f32_16x16x32_bf16 v[56:59], v[162:165], v[222:225], v[56:59]
	v_mfma_f32_16x16x32_bf16 v[48:51], v[154:157], v[230:233], v[48:51]
	v_mfma_f32_16x16x32_bf16 v[40:43], v[162:165], v[230:233], v[40:43]
	v_mfma_f32_16x16x32_bf16 v[36:39], v[154:157], v[238:241], v[36:39]
	v_mfma_f32_16x16x32_bf16 v[32:35], v[162:165], v[238:241], v[32:35]
	v_mfma_f32_16x16x32_bf16 v[68:71], v[158:161], v[218:221], v[68:71]
	v_mfma_f32_16x16x32_bf16 v[64:67], v[194:197], v[218:221], v[64:67]
	v_mfma_f32_16x16x32_bf16 v[60:63], v[158:161], v[226:229], v[60:63]
	v_mfma_f32_16x16x32_bf16 v[56:59], v[194:197], v[226:229], v[56:59]
	v_mfma_f32_16x16x32_bf16 v[48:51], v[158:161], v[234:237], v[48:51]
	v_mfma_f32_16x16x32_bf16 v[40:43], v[194:197], v[234:237], v[40:43]
	v_mfma_f32_16x16x32_bf16 v[36:39], v[158:161], v[242:245], v[36:39]
	v_mfma_f32_16x16x32_bf16 v[32:35], v[194:197], v[242:245], v[32:35]
	s_setprio 0
	s_setprio 1
	v_mfma_f32_16x16x32_bf16 v[28:31], v[198:201], v[214:217], v[28:31]
	v_mfma_f32_16x16x32_bf16 v[24:27], v[206:209], v[214:217], v[24:27]
	v_mfma_f32_16x16x32_bf16 v[20:23], v[198:201], v[222:225], v[20:23]
	v_mfma_f32_16x16x32_bf16 v[16:19], v[206:209], v[222:225], v[16:19]
	v_mfma_f32_16x16x32_bf16 v[12:15], v[198:201], v[230:233], v[12:15]
	v_mfma_f32_16x16x32_bf16 v[8:11], v[206:209], v[230:233], v[8:11]
	v_mfma_f32_16x16x32_bf16 v[4:7], v[198:201], v[238:241], v[4:7]
	v_mfma_f32_16x16x32_bf16 v[0:3], v[206:209], v[238:241], v[0:3]
	v_mfma_f32_16x16x32_bf16 v[28:31], v[202:205], v[218:221], v[28:31]
	v_mfma_f32_16x16x32_bf16 v[24:27], v[210:213], v[218:221], v[24:27]
	v_mfma_f32_16x16x32_bf16 v[20:23], v[202:205], v[226:229], v[20:23]
	v_mfma_f32_16x16x32_bf16 v[16:19], v[210:213], v[226:229], v[16:19]
	v_mfma_f32_16x16x32_bf16 v[12:15], v[202:205], v[234:237], v[12:15]
	v_mfma_f32_16x16x32_bf16 v[8:11], v[210:213], v[234:237], v[8:11]
	v_mfma_f32_16x16x32_bf16 v[4:7], v[202:205], v[242:245], v[4:7]
	v_mfma_f32_16x16x32_bf16 v[0:3], v[210:213], v[242:245], v[0:3]
	s_setprio 0
	s_barrier
	ds_read_b128 v[154:157], v146
	ds_read_b128 v[158:161], v147
	ds_read_b128 v[162:165], v148
	ds_read_b128 v[194:197], v149
	ds_read_b128 v[198:201], v150
	ds_read_b128 v[202:205], v151
	ds_read_b128 v[206:209], v152
	ds_read_b128 v[210:213], v153
	s_add_u32 s26, s26, 0x40000
	s_addc_u32 s27, s27, 0
	s_mov_b32 m0, s28
	v_lshl_add_u64 v[180:181], s[26:27], 0, v[168:169]
	ds_read_b128 v[214:217], v137 offset:32768
	ds_read_b128 v[218:221], v137 offset:33792
	ds_read_b128 v[222:225], v137 offset:34816
	ds_read_b128 v[226:229], v137 offset:35840
	ds_read_b128 v[230:233], v137 offset:36864
	ds_read_b128 v[234:237], v137 offset:37888
	ds_read_b128 v[238:241], v137 offset:38912
	ds_read_b128 v[242:245], v137 offset:39936
	global_load_lds_dwordx4 v[180:181], off
	v_lshl_add_u64 v[180:181], s[26:27], 0, v[128:129]
	s_mov_b32 m0, s29
	s_nop 0
	global_load_lds_dwordx4 v[180:181], off
	s_waitcnt vmcnt(8)
	s_waitcnt lgkmcnt(0)
	s_barrier
	s_setprio 1
	s_waitcnt lgkmcnt(0)
	v_mfma_f32_16x16x32_bf16 v[124:127], v[154:157], v[214:217], v[124:127]
	v_mfma_f32_16x16x32_bf16 v[120:123], v[162:165], v[214:217], v[120:123]
	v_mfma_f32_16x16x32_bf16 v[116:119], v[154:157], v[222:225], v[116:119]
	v_mfma_f32_16x16x32_bf16 v[112:115], v[162:165], v[222:225], v[112:115]
	v_mfma_f32_16x16x32_bf16 v[108:111], v[154:157], v[230:233], v[108:111]
	v_mfma_f32_16x16x32_bf16 v[104:107], v[162:165], v[230:233], v[104:107]
	v_mfma_f32_16x16x32_bf16 v[76:79], v[154:157], v[238:241], v[76:79]
	v_mfma_f32_16x16x32_bf16 v[72:75], v[162:165], v[238:241], v[72:75]
	v_mfma_f32_16x16x32_bf16 v[124:127], v[158:161], v[218:221], v[124:127]
	v_mfma_f32_16x16x32_bf16 v[120:123], v[194:197], v[218:221], v[120:123]
	v_mfma_f32_16x16x32_bf16 v[116:119], v[158:161], v[226:229], v[116:119]
	v_mfma_f32_16x16x32_bf16 v[112:115], v[194:197], v[226:229], v[112:115]
	v_mfma_f32_16x16x32_bf16 v[108:111], v[158:161], v[234:237], v[108:111]
	v_mfma_f32_16x16x32_bf16 v[104:107], v[194:197], v[234:237], v[104:107]
	v_mfma_f32_16x16x32_bf16 v[76:79], v[158:161], v[242:245], v[76:79]
	v_mfma_f32_16x16x32_bf16 v[72:75], v[194:197], v[242:245], v[72:75]
	s_setprio 0
	s_setprio 1
	v_mfma_f32_16x16x32_bf16 v[100:103], v[198:201], v[214:217], v[100:103]
	v_mfma_f32_16x16x32_bf16 v[96:99], v[206:209], v[214:217], v[96:99]
	v_mfma_f32_16x16x32_bf16 v[92:95], v[198:201], v[222:225], v[92:95]
	v_mfma_f32_16x16x32_bf16 v[88:91], v[206:209], v[222:225], v[88:91]
	v_mfma_f32_16x16x32_bf16 v[84:87], v[198:201], v[230:233], v[84:87]
	v_mfma_f32_16x16x32_bf16 v[80:83], v[206:209], v[230:233], v[80:83]
	v_mfma_f32_16x16x32_bf16 v[52:55], v[198:201], v[238:241], v[52:55]
	v_mfma_f32_16x16x32_bf16 v[44:47], v[206:209], v[238:241], v[44:47]
	v_mfma_f32_16x16x32_bf16 v[100:103], v[202:205], v[218:221], v[100:103]
	v_mfma_f32_16x16x32_bf16 v[96:99], v[210:213], v[218:221], v[96:99]
	v_mfma_f32_16x16x32_bf16 v[92:95], v[202:205], v[226:229], v[92:95]
	v_mfma_f32_16x16x32_bf16 v[88:91], v[210:213], v[226:229], v[88:91]
	v_mfma_f32_16x16x32_bf16 v[84:87], v[202:205], v[234:237], v[84:87]
	v_mfma_f32_16x16x32_bf16 v[80:83], v[210:213], v[234:237], v[80:83]
	v_mfma_f32_16x16x32_bf16 v[52:55], v[202:205], v[242:245], v[52:55]
	v_mfma_f32_16x16x32_bf16 v[44:47], v[210:213], v[242:245], v[44:47]
	s_setprio 0
	s_barrier
	s_mov_b32 m0, s19
	v_lshl_add_u64 v[166:167], v[166:167], 0, s[34:35]
	s_add_u32 s14, s14, 0x40080
	ds_read_b128 v[214:217], v137 offset:49152
	ds_read_b128 v[218:221], v137 offset:50176
	ds_read_b128 v[222:225], v137 offset:51200
	ds_read_b128 v[226:229], v137 offset:52224
	ds_read_b128 v[230:233], v137 offset:53248
	ds_read_b128 v[234:237], v137 offset:54272
	ds_read_b128 v[238:241], v137 offset:55296
	ds_read_b128 v[242:245], v137 offset:56320
	global_load_lds_dwordx4 v[166:167], off
	v_lshl_add_u64 v[166:167], v[246:247], 0, s[34:35]
	s_mov_b32 m0, s30
	s_addc_u32 s15, s15, 0
	global_load_lds_dwordx4 v[166:167], off
	v_lshl_add_u64 v[166:167], s[14:15], 0, v[168:169]
	s_mov_b32 m0, s63
	s_nop 0
	global_load_lds_dwordx4 v[166:167], off
	v_lshl_add_u64 v[166:167], s[14:15], 0, v[128:129]
	s_mov_b32 m0, s24
	s_nop 0
	global_load_lds_dwordx4 v[166:167], off
	v_lshl_add_u64 v[166:167], v[248:249], 0, s[34:35]
	s_mov_b32 m0, s61
	s_nop 0
	global_load_lds_dwordx4 v[166:167], off
	v_lshl_add_u64 v[166:167], v[250:251], 0, s[34:35]
	s_mov_b32 m0, s62
	s_nop 0
	global_load_lds_dwordx4 v[166:167], off
	s_waitcnt vmcnt(8)
	s_waitcnt lgkmcnt(0)
	s_barrier
	s_setprio 1
	s_waitcnt lgkmcnt(0)
	v_mfma_f32_16x16x32_bf16 v[68:71], v[154:157], v[214:217], v[68:71]
	v_mfma_f32_16x16x32_bf16 v[64:67], v[162:165], v[214:217], v[64:67]
	v_mfma_f32_16x16x32_bf16 v[60:63], v[154:157], v[222:225], v[60:63]
	v_mfma_f32_16x16x32_bf16 v[56:59], v[162:165], v[222:225], v[56:59]
	v_mfma_f32_16x16x32_bf16 v[48:51], v[154:157], v[230:233], v[48:51]
	v_mfma_f32_16x16x32_bf16 v[40:43], v[162:165], v[230:233], v[40:43]
	v_mfma_f32_16x16x32_bf16 v[36:39], v[154:157], v[238:241], v[36:39]
	v_mfma_f32_16x16x32_bf16 v[32:35], v[162:165], v[238:241], v[32:35]
	v_mfma_f32_16x16x32_bf16 v[68:71], v[158:161], v[218:221], v[68:71]
	v_mfma_f32_16x16x32_bf16 v[64:67], v[194:197], v[218:221], v[64:67]
	v_mfma_f32_16x16x32_bf16 v[60:63], v[158:161], v[226:229], v[60:63]
	v_mfma_f32_16x16x32_bf16 v[56:59], v[194:197], v[226:229], v[56:59]
	v_mfma_f32_16x16x32_bf16 v[48:51], v[158:161], v[234:237], v[48:51]
	v_mfma_f32_16x16x32_bf16 v[40:43], v[194:197], v[234:237], v[40:43]
	v_mfma_f32_16x16x32_bf16 v[36:39], v[158:161], v[242:245], v[36:39]
	v_mfma_f32_16x16x32_bf16 v[32:35], v[194:197], v[242:245], v[32:35]
	s_setprio 0
	s_setprio 1
	v_mfma_f32_16x16x32_bf16 v[28:31], v[198:201], v[214:217], v[28:31]
	v_mfma_f32_16x16x32_bf16 v[24:27], v[206:209], v[214:217], v[24:27]
	v_mfma_f32_16x16x32_bf16 v[20:23], v[198:201], v[222:225], v[20:23]
	v_mfma_f32_16x16x32_bf16 v[16:19], v[206:209], v[222:225], v[16:19]
	v_mfma_f32_16x16x32_bf16 v[12:15], v[198:201], v[230:233], v[12:15]
	v_mfma_f32_16x16x32_bf16 v[8:11], v[206:209], v[230:233], v[8:11]
	v_mfma_f32_16x16x32_bf16 v[4:7], v[198:201], v[238:241], v[4:7]
	v_mfma_f32_16x16x32_bf16 v[0:3], v[206:209], v[238:241], v[0:3]
	v_mfma_f32_16x16x32_bf16 v[28:31], v[202:205], v[218:221], v[28:31]
	v_mfma_f32_16x16x32_bf16 v[24:27], v[210:213], v[218:221], v[24:27]
	v_mfma_f32_16x16x32_bf16 v[20:23], v[202:205], v[226:229], v[20:23]
	v_mfma_f32_16x16x32_bf16 v[16:19], v[210:213], v[226:229], v[16:19]
	v_mfma_f32_16x16x32_bf16 v[12:15], v[202:205], v[234:237], v[12:15]
	v_mfma_f32_16x16x32_bf16 v[8:11], v[210:213], v[234:237], v[8:11]
	v_mfma_f32_16x16x32_bf16 v[4:7], v[202:205], v[242:245], v[4:7]
	v_mfma_f32_16x16x32_bf16 v[0:3], v[210:213], v[242:245], v[0:3]
	s_setprio 0
	s_barrier
	s_add_i32 s60, s60, 2
	s_add_u32 s88, s88, 0x100
	s_addc_u32 s89, s89, 0
	s_cmp_lt_u32 s60, 14
	s_cbranch_scc1 .LBB0_24
	v_lshlrev_b32_e32 v160, 3, v192
	s_lshl_b32 s14, s40, 7
	v_and_b32_e32 v160, 0x78, v160
	v_or_b32_e32 v160, s14, v160
	v_ashrrev_i32_e32 v161, 31, v160
	v_readlane_b32 s14, v255, 16
	v_readlane_b32 s15, v255, 17
	v_lshlrev_b64 v[160:161], 2, v[160:161]
	s_nop 1
	v_lshl_add_u64 v[162:163], s[56:57], 0, v[160:161]
	v_lshl_add_u64 v[164:165], s[44:45], 0, v[160:161]
	v_lshl_add_u64 v[166:167], s[14:15], 0, v[160:161]
	v_lshl_add_u64 v[160:161], s[54:55], 0, v[160:161]
	global_load_dwordx4 v[194:197], v[162:163], off offset:16
	global_load_dwordx4 v[210:213], v[162:163], off
	global_load_dwordx4 v[198:201], v[164:165], off offset:16
	global_load_dwordx4 v[214:217], v[164:165], off
	global_load_dwordx4 v[202:205], v[166:167], off offset:16
	global_load_dwordx4 v[218:221], v[166:167], off
	global_load_dwordx4 v[206:209], v[160:161], off offset:16
	global_load_dwordx4 v[222:225], v[160:161], off
	s_waitcnt vmcnt(0)
	s_cmpk_gt_u32 s92, 0xff
	s_cbranch_scc1 .LBB0_27
	s_barrier

.LBB0_29:
	s_or_b64 exec, exec, s[14:15]
	v_mov_b32_e32 v114, v192
	s_waitcnt lgkmcnt(0)
	s_barrier
	s_lshl_b32 s26, s40, 7
	v_lshlrev_b32_e32 v80, 3, v114
	v_and_b32_e32 v115, 0x78, v80
	v_or_b32_e32 v112, s26, v115
	v_ashrrev_i32_e32 v113, 31, v112
	s_mov_b64 s[52:53], s[44:45]
	v_readlane_b32 s44, v255, 16
	v_lshlrev_b64 v[92:93], 2, v[112:113]
	v_readlane_b32 s45, v255, 17
	v_lshl_add_u64 v[84:85], s[56:57], 0, v[92:93]
	v_lshl_add_u64 v[88:89], s[52:53], 0, v[92:93]
	v_lshl_add_u64 v[94:95], s[44:45], 0, v[92:93]
	v_lshl_add_u64 v[108:109], s[48:49], 0, v[92:93]
	v_mov_b64_e32 v[80:81], v[194:195]
	v_mov_b64_e32 v[82:83], v[196:197]
	v_mov_b64_e32 v[84:85], v[198:199]
	v_mov_b64_e32 v[86:87], v[200:201]
	v_mov_b64_e32 v[88:89], v[202:203]
	v_mov_b64_e32 v[90:91], v[204:205]
	v_mov_b64_e32 v[92:93], v[206:207]
	v_mov_b64_e32 v[94:95], v[208:209]
	v_mov_b64_e32 v[96:97], v[210:211]
	v_mov_b64_e32 v[98:99], v[212:213]
	v_mov_b64_e32 v[100:101], v[214:215]
	v_mov_b64_e32 v[102:103], v[216:217]
	v_mov_b64_e32 v[104:105], v[218:219]
	v_mov_b64_e32 v[106:107], v[220:221]
	v_mov_b64_e32 v[108:109], v[222:223]
	v_mov_b64_e32 v[110:111], v[224:225]
	v_ashrrev_i32_e32 v116, 4, v114
	v_lshrrev_b32_e32 v114, 4, v114
	v_bfi_b32 v118, -4, v116, v114
	s_movk_i32 s5, 0x7f
	v_add_u32_e32 v114, s91, v118
	v_cmp_gt_i32_e32 vcc, s5, v118
	s_mov_b32 s5, 0x14000
	v_cmp_gt_i32_e64 s[40:41], s5, v114
	s_movk_i32 s5, 0x410
	v_lshlrev_b32_e32 v116, 2, v115
	v_mul_lo_u32 v117, v118, s5
	s_and_b64 s[28:29], vcc, s[40:41]
	v_add_u32_e32 v120, v116, v117
	v_lshl_add_u32 v119, v115, 2, v117
	s_and_saveexec_b64 s[14:15], s[28:29]
	s_mov_b32 s92, 0
	s_mov_b32 s93, 0x403e0000
	s_cbranch_execz .LBB0_31
	v_cmp_gt_i32_e32 vcc, s33, v114
	ds_read_b128 v[122:125], v120
	ds_read_b128 v[130:133], v120 offset:16
	ds_read_b128 v[136:139], v119 offset:1040
	ds_read_b128 v[140:143], v119 offset:1056
	ds_read_b128 v[144:147], v119 offset:2080
	ds_read_b128 v[148:151], v119 offset:2096
	ds_read_b128 v[152:155], v119 offset:1552
	ds_read_b128 v[156:159], v119 offset:1568
	v_cndmask_b32_e32 v115, v178, v179, vcc
	v_and_b32_e32 v115, v115, v114
	v_cndmask_b32_e32 v121, v175, v176, vcc
	v_cmp_ne_u32_e32 vcc, 0, v115
	v_add_u32_e32 v115, 1, v115
	s_mov_b32 s24, 0xc0135761
	s_waitcnt lgkmcnt(6)
	v_cndmask_b32_e32 v127, 0, v133, vcc
	v_cndmask_b32_e32 v126, 0, v132, vcc
	v_cndmask_b32_e32 v131, 0, v131, vcc
	v_cndmask_b32_e32 v130, 0, v130, vcc
	v_cndmask_b32_e32 v125, 0, v125, vcc
	v_cndmask_b32_e32 v124, 0, v124, vcc
	v_cndmask_b32_e32 v123, 0, v123, vcc
	v_cndmask_b32_e32 v122, 0, v122, vcc
	v_cmp_lt_u32_e32 vcc, v115, v121
	v_ashrrev_i32_e32 v115, 31, v114
	v_lshlrev_b64 v[114:115], 13, v[114:115]
	s_waitcnt lgkmcnt(3)
	v_cndmask_b32_e32 v145, 0, v145, vcc
	v_cndmask_b32_e32 v144, 0, v144, vcc
	v_pk_fma_f32 v[144:145], v[104:105], v[144:145], v[108:109]
	v_cndmask_b32_e32 v147, 0, v147, vcc
	v_pk_fma_f32 v[136:137], v[100:101], v[136:137], v[144:145]
	v_mov_b64_e32 v[144:145], s[24:25]
	v_pk_fma_f32 v[122:123], v[96:97], v[122:123], v[136:137]
	s_mov_b32 s24, 0x3dd2d3e8
	v_pk_mul_f32 v[136:137], v[122:123], v[122:123]
	v_cndmask_b32_e32 v146, 0, v146, vcc
	v_pk_fma_f32 v[136:137], v[136:137], s[24:25], v[144:145] op_sel_hi:[1,0,0] neg_lo:[1,0,0] neg_hi:[1,0,0]
	s_waitcnt lgkmcnt(2)
	v_cndmask_b32_e32 v133, 0, v151, vcc
	v_pk_mul_f32 v[136:137], v[122:123], v[136:137]
	v_cndmask_b32_e32 v132, 0, v150, vcc
	v_exp_f32_e32 v136, v136
	v_exp_f32_e32 v137, v137
	v_cndmask_b32_e32 v149, 0, v149, vcc
	v_cndmask_b32_e32 v148, 0, v148, vcc
	v_pk_fma_f32 v[132:133], v[90:91], v[132:133], v[94:95]
	v_pk_add_f32 v[136:137], v[136:137], 1.0 op_sel_hi:[1,0]
	v_pk_fma_f32 v[132:133], v[86:87], v[142:143], v[132:133]
	v_rcp_f32_e32 v136, v136
	v_rcp_f32_e32 v137, v137
	v_pk_fma_f32 v[126:127], v[82:83], v[126:127], v[132:133]
	v_lshl_add_u64 v[114:115], s[46:47], 0, v[114:115]
	v_pk_mul_f32 v[132:133], v[126:127], v[126:127]
	v_pk_mul_f32 v[122:123], v[122:123], v[136:137]
	v_pk_fma_f32 v[136:137], v[106:107], v[146:147], v[110:111]
	v_pk_fma_f32 v[132:133], v[132:133], s[24:25], v[144:145] op_sel_hi:[1,0,0] neg_lo:[1,0,0] neg_hi:[1,0,0]
	v_pk_fma_f32 v[136:137], v[102:103], v[138:139], v[136:137]
	v_pk_mul_f32 v[132:133], v[126:127], v[132:133]
	v_pk_fma_f32 v[124:125], v[98:99], v[124:125], v[136:137]
	v_exp_f32_e32 v132, v132
	v_pk_mul_f32 v[136:137], v[124:125], v[124:125]
	v_exp_f32_e32 v133, v133
	v_pk_fma_f32 v[136:137], v[136:137], s[24:25], v[144:145] op_sel_hi:[1,0,0] neg_lo:[1,0,0] neg_hi:[1,0,0]
	s_waitcnt lgkmcnt(1)
	v_pk_mul_f32 v[122:123], v[152:153], v[122:123]
	v_pk_mul_f32 v[136:137], v[124:125], v[136:137]
	v_pk_add_f32 v[132:133], v[132:133], 1.0 op_sel_hi:[1,0]
	v_exp_f32_e32 v136, v136
	v_exp_f32_e32 v137, v137
	v_rcp_f32_e32 v132, v132
	v_rcp_f32_e32 v133, v133
	v_cvt_pk_bf16_f32 v122, v122, v123
	v_pk_add_f32 v[136:137], v[136:137], 1.0 op_sel_hi:[1,0]
	v_lshl_add_u64 v[114:115], v[112:113], 1, v[114:115]
	v_rcp_f32_e32 v136, v136
	v_rcp_f32_e32 v137, v137
	v_pk_mul_f32 v[126:127], v[126:127], v[132:133]
	v_pk_mul_f32 v[124:125], v[124:125], v[136:137]
	v_pk_fma_f32 v[136:137], v[88:89], v[148:149], v[92:93]
	v_pk_mul_f32 v[124:125], v[154:155], v[124:125]
	v_pk_fma_f32 v[136:137], v[84:85], v[140:141], v[136:137]
	s_waitcnt lgkmcnt(0)
	v_pk_mul_f32 v[126:127], v[158:159], v[126:127]
	v_pk_fma_f32 v[130:131], v[80:81], v[130:131], v[136:137]
	v_cvt_pk_bf16_f32 v123, v124, v125
	v_pk_mul_f32 v[136:137], v[130:131], v[130:131]
	v_cvt_pk_bf16_f32 v125, v126, v127
	v_pk_fma_f32 v[136:137], v[136:137], s[24:25], v[144:145] op_sel_hi:[1,0,0] neg_lo:[1,0,0] neg_hi:[1,0,0]
	s_nop 0
	v_pk_mul_f32 v[136:137], v[130:131], v[136:137]
	s_nop 0
	v_exp_f32_e32 v136, v136
	v_exp_f32_e32 v137, v137
	s_nop 0
	v_pk_add_f32 v[136:137], v[136:137], 1.0 op_sel_hi:[1,0]
	s_nop 0
	v_rcp_f32_e32 v136, v136
	v_rcp_f32_e32 v137, v137
	s_nop 0
	v_pk_mul_f32 v[130:131], v[130:131], v[136:137]
	s_nop 0
	v_pk_mul_f32 v[130:131], v[156:157], v[130:131]
	s_nop 0
	v_cvt_pk_bf16_f32 v124, v130, v131
	global_store_dwordx4 v[114:115], v[122:125], off

.LBB0_39:
	s_or_b64 exec, exec, s[14:15]
	v_mov_b32_e32 v34, v192
	s_waitcnt lgkmcnt(0)
	s_barrier
	s_add_i32 s5, s91, 0x7f
	v_lshlrev_b32_e32 v0, 3, v34
	v_and_b32_e32 v36, 0x78, v0
	v_or_b32_e32 v32, s26, v36
	v_ashrrev_i32_e32 v33, 31, v32
	v_lshlrev_b64 v[12:13], 2, v[32:33]
	v_lshl_add_u64 v[4:5], s[56:57], 0, v[12:13]
	v_lshl_add_u64 v[8:9], s[52:53], 0, v[12:13]
	v_lshl_add_u64 v[14:15], s[44:45], 0, v[12:13]
	v_lshl_add_u64 v[28:29], s[48:49], 0, v[12:13]
	v_mov_b64_e32 v[0:1], v[194:195]
	v_mov_b64_e32 v[2:3], v[196:197]
	v_mov_b64_e32 v[4:5], v[198:199]
	v_mov_b64_e32 v[6:7], v[200:201]
	v_mov_b64_e32 v[8:9], v[202:203]
	v_mov_b64_e32 v[10:11], v[204:205]
	v_mov_b64_e32 v[12:13], v[206:207]
	v_mov_b64_e32 v[14:15], v[208:209]
	v_mov_b64_e32 v[16:17], v[210:211]
	v_mov_b64_e32 v[18:19], v[212:213]
	v_mov_b64_e32 v[20:21], v[214:215]
	v_mov_b64_e32 v[22:23], v[216:217]
	v_mov_b64_e32 v[24:25], v[218:219]
	v_mov_b64_e32 v[26:27], v[220:221]
	v_mov_b64_e32 v[28:29], v[222:223]
	v_mov_b64_e32 v[30:31], v[224:225]
	v_ashrrev_i32_e32 v35, 4, v34
	v_lshrrev_b32_e32 v34, 4, v34
	v_bfi_b32 v39, -4, v35, v34
	v_add_u32_e32 v34, s5, v39
	s_movk_i32 s5, 0x7f
	v_cmp_gt_i32_e32 vcc, s5, v39
	s_mov_b32 s5, 0x14000
	v_cmp_gt_i32_e64 s[40:41], s5, v34
	s_movk_i32 s5, 0x410
	v_lshlrev_b32_e32 v37, 2, v36
	s_and_b64 s[26:27], vcc, s[40:41]
	v_mul_lo_u32 v38, v39, s5
	s_and_saveexec_b64 s[14:15], s[26:27]
	s_cbranch_execz .Lp4_skip_b0
	v_add_u32_e32 v44, v37, v38
	ds_read_b128 v[40:43], v44
	ds_read_b128 v[44:47], v44 offset:16
	v_cmp_gt_i32_e32 vcc, s33, v34
	v_lshl_add_u32 v68, v36, 2, v38
	ds_read_b128 v[48:51], v68 offset:1040
	ds_read_b128 v[52:55], v68 offset:1056
	ds_read_b128 v[56:59], v68 offset:2080
	ds_read_b128 v[60:63], v68 offset:2096
	ds_read_b128 v[64:67], v68 offset:1552
	ds_read_b128 v[68:71], v68 offset:1568
	v_cndmask_b32_e32 v35, v178, v179, vcc
	v_and_b32_e32 v35, v35, v34
	v_cndmask_b32_e32 v72, v175, v176, vcc
	v_cmp_ne_u32_e32 vcc, 0, v35
	v_add_u32_e32 v35, 1, v35
	s_mov_b32 s24, 0xc0135761
	s_waitcnt lgkmcnt(6)
	v_cndmask_b32_e32 v47, 0, v47, vcc
	v_cndmask_b32_e32 v46, 0, v46, vcc
	v_cndmask_b32_e32 v45, 0, v45, vcc
	v_cndmask_b32_e32 v44, 0, v44, vcc
	v_cndmask_b32_e32 v43, 0, v43, vcc
	v_cndmask_b32_e32 v42, 0, v42, vcc
	v_cndmask_b32_e32 v41, 0, v41, vcc
	v_cndmask_b32_e32 v40, 0, v40, vcc
	v_cmp_lt_u32_e32 vcc, v35, v72
	v_ashrrev_i32_e32 v35, 31, v34
	v_lshlrev_b64 v[34:35], 13, v[34:35]
	s_waitcnt lgkmcnt(3)
	v_cndmask_b32_e32 v57, 0, v57, vcc
	v_cndmask_b32_e32 v56, 0, v56, vcc
	v_pk_fma_f32 v[56:57], v[24:25], v[56:57], v[28:29]
	v_cndmask_b32_e32 v59, 0, v59, vcc
	v_pk_fma_f32 v[48:49], v[20:21], v[48:49], v[56:57]
	v_mov_b64_e32 v[56:57], s[24:25]
	v_pk_fma_f32 v[40:41], v[16:17], v[40:41], v[48:49]
	s_mov_b32 s24, 0x3dd2d3e8
	v_pk_mul_f32 v[48:49], v[40:41], v[40:41]
	v_cndmask_b32_e32 v58, 0, v58, vcc
	v_pk_fma_f32 v[48:49], v[48:49], s[24:25], v[56:57] op_sel_hi:[1,0,0] neg_lo:[1,0,0] neg_hi:[1,0,0]
	s_waitcnt lgkmcnt(2)
	v_cndmask_b32_e32 v61, 0, v61, vcc
	v_pk_mul_f32 v[48:49], v[40:41], v[48:49]
	v_cndmask_b32_e32 v60, 0, v60, vcc
	v_exp_f32_e32 v48, v48
	v_exp_f32_e32 v49, v49
	v_cndmask_b32_e32 v63, 0, v63, vcc
	v_cndmask_b32_e32 v62, 0, v62, vcc
	v_lshl_add_u64 v[34:35], s[46:47], 0, v[34:35]
	v_pk_add_f32 v[48:49], v[48:49], 1.0 op_sel_hi:[1,0]
	v_lshl_add_u64 v[34:35], v[32:33], 1, v[34:35]
	v_rcp_f32_e32 v48, v48
	v_rcp_f32_e32 v49, v49
	s_nop 0
	v_pk_mul_f32 v[40:41], v[40:41], v[48:49]
	v_pk_fma_f32 v[48:49], v[26:27], v[58:59], v[30:31]
	s_waitcnt lgkmcnt(1)
	v_pk_mul_f32 v[40:41], v[64:65], v[40:41]
	v_pk_fma_f32 v[48:49], v[22:23], v[50:51], v[48:49]
	v_cvt_pk_bf16_f32 v40, v40, v41
	v_pk_fma_f32 v[42:43], v[18:19], v[42:43], v[48:49]
	s_nop 0
	v_pk_mul_f32 v[48:49], v[42:43], v[42:43]
	s_nop 0
	v_pk_fma_f32 v[48:49], v[48:49], s[24:25], v[56:57] op_sel_hi:[1,0,0] neg_lo:[1,0,0] neg_hi:[1,0,0]
	s_nop 0
	v_pk_mul_f32 v[48:49], v[42:43], v[48:49]
	s_nop 0
	v_exp_f32_e32 v48, v48
	v_exp_f32_e32 v49, v49
	s_nop 0
	v_pk_add_f32 v[48:49], v[48:49], 1.0 op_sel_hi:[1,0]
	s_nop 0
	v_rcp_f32_e32 v48, v48
	v_rcp_f32_e32 v49, v49
	s_nop 0
	v_pk_mul_f32 v[42:43], v[42:43], v[48:49]
	v_pk_fma_f32 v[48:49], v[8:9], v[60:61], v[12:13]
	v_pk_mul_f32 v[42:43], v[66:67], v[42:43]
	v_pk_fma_f32 v[48:49], v[4:5], v[52:53], v[48:49]
	v_cvt_pk_bf16_f32 v41, v42, v43
	v_pk_fma_f32 v[44:45], v[0:1], v[44:45], v[48:49]
	s_nop 0
	v_pk_mul_f32 v[48:49], v[44:45], v[44:45]
	s_nop 0
	v_pk_fma_f32 v[48:49], v[48:49], s[24:25], v[56:57] op_sel_hi:[1,0,0] neg_lo:[1,0,0] neg_hi:[1,0,0]
	s_nop 0
	v_pk_mul_f32 v[48:49], v[44:45], v[48:49]
	s_nop 0
	v_exp_f32_e32 v48, v48
	v_exp_f32_e32 v49, v49
	s_nop 0
	v_pk_add_f32 v[48:49], v[48:49], 1.0 op_sel_hi:[1,0]
	s_nop 0
	v_rcp_f32_e32 v48, v48
	v_rcp_f32_e32 v49, v49
	s_nop 0
	v_pk_mul_f32 v[44:45], v[44:45], v[48:49]
	v_pk_fma_f32 v[48:49], v[10:11], v[62:63], v[14:15]
	s_waitcnt lgkmcnt(0)
	v_pk_mul_f32 v[44:45], v[68:69], v[44:45]
	v_pk_fma_f32 v[48:49], v[6:7], v[54:55], v[48:49]
	v_cvt_pk_bf16_f32 v42, v44, v45
	v_pk_fma_f32 v[46:47], v[2:3], v[46:47], v[48:49]
	s_nop 0
	v_pk_mul_f32 v[48:49], v[46:47], v[46:47]
	s_nop 0
	v_pk_fma_f32 v[48:49], v[48:49], s[24:25], v[56:57] op_sel_hi:[1,0,0] neg_lo:[1,0,0] neg_hi:[1,0,0]
	s_nop 0
	v_pk_mul_f32 v[48:49], v[46:47], v[48:49]
	s_nop 0
	v_exp_f32_e32 v48, v48
	v_exp_f32_e32 v49, v49
	s_nop 0
	v_pk_add_f32 v[48:49], v[48:49], 1.0 op_sel_hi:[1,0]
	s_nop 0
	v_rcp_f32_e32 v48, v48
	v_rcp_f32_e32 v49, v49
	s_nop 0
	v_pk_mul_f32 v[46:47], v[46:47], v[48:49]
	s_nop 0
	v_pk_mul_f32 v[46:47], v[70:71], v[46:47]
	s_nop 0
	v_cvt_pk_bf16_f32 v43, v46, v47
	global_store_dwordx4 v[34:35], v[40:43], off

.Lp4_skip_b0:
	s_waitcnt vmcnt(0)
	s_branch .LBB0_41
	s_nop 0
	s_nop 0
	s_nop 0
	s_nop 0
	s_nop 0
	s_nop 0
	s_nop 0
	s_nop 0
	s_nop 0
	s_nop 0
	s_nop 0
	s_nop 0
	s_nop 0
	s_nop 0
	s_nop 0

.LBB0_49:
	v_readlane_b32 s5, v252, 13
	s_waitcnt vmcnt(6)
	s_nop 0
	v_add_u32_e32 v16, s5, v191
	s_mov_b32 s5, 0x14000
	v_cmp_gt_i32_e32 vcc, s5, v16
	s_and_saveexec_b64 s[26:27], vcc
	s_cbranch_execz .LBB0_58
	v_and_b32_e32 v0, 64, v182
	v_add_u32_e32 v0, 64, v0
	v_xor_b32_e32 v1, 32, v182
	v_cmp_lt_i32_e32 vcc, v1, v0
	s_cmp_lg_u32 s16, 7
	v_readlane_b32 s28, v255, 26
	v_cndmask_b32_e32 v1, v182, v1, vcc
	s_waitcnt vmcnt(0)
	v_lshlrev_b32_e32 v30, 2, v1
	v_xor_b32_e32 v1, 16, v182
	v_cmp_lt_i32_e32 vcc, v1, v0
	s_cselect_b64 s[14:15], -1, 0
	v_readlane_b32 s29, v255, 27
	v_cndmask_b32_e32 v1, v182, v1, vcc
	v_lshlrev_b32_e32 v31, 2, v1
	v_xor_b32_e32 v1, 8, v182
	v_cmp_lt_i32_e32 vcc, v1, v0
	s_cmp_lg_u32 s28, 1
	s_mov_b32 s24, s28
	v_cndmask_b32_e32 v1, v182, v1, vcc
	s_cselect_b64 s[28:29], -1, 0
	v_lshlrev_b32_e32 v32, 2, v1
	v_xor_b32_e32 v1, 4, v182
	s_or_b64 s[44:45], s[28:29], s[14:15]
	v_readlane_b32 s14, v255, 32
	v_readlane_b32 s52, v254, 7
	v_readlane_b32 s68, v254, 23
	v_cmp_lt_i32_e32 vcc, v1, v0
	s_cmp_eq_u32 s16, 4
	v_readlane_b32 s15, v255, 33
	v_readlane_b32 s56, v254, 11
	v_readlane_b32 s57, v254, 12
	v_readlane_b32 s74, v254, 29
	v_readlane_b32 s75, v254, 30
	v_cndmask_b32_e32 v1, v182, v1, vcc
	s_cselect_b32 s15, s15, s18
	s_cselect_b32 s14, s14, s17
	s_cselect_b32 s5, s75, s57
	s_cselect_b32 s19, s74, s56
	s_lshl_b32 s28, s24, 10
	v_lshlrev_b32_e32 v33, 2, v1
	v_xor_b32_e32 v1, 2, v182
	s_ashr_i32 s29, s28, 31
	v_cmp_lt_i32_e32 vcc, v1, v0
	s_lshl_b64 s[28:29], s[28:29], 2
	s_add_u32 s28, s19, s28
	v_cndmask_b32_e32 v1, v182, v1, vcc
	v_lshlrev_b32_e32 v34, 2, v1
	v_xor_b32_e32 v1, 1, v182
	s_addc_u32 s29, s5, s29
	v_cmp_lt_i32_e32 vcc, v1, v0
	v_lshlrev_b32_e32 v168, 4, v170
	v_lshl_add_u64 v[18:19], s[28:29], 0, v[168:169]
	v_cndmask_b32_e32 v0, v182, v1, vcc
	v_readlane_b32 s28, v253, 35
	v_ashrrev_i32_e32 v17, 31, v16
	v_readlane_b32 s53, v254, 8
	v_lshlrev_b32_e32 v35, 2, v0
	v_readlane_b32 s29, v253, 36
	v_lshlrev_b64 v[0:1], 11, v[16:17]
	s_nor_b64 s[52:53], s[44:45], s[28:29]
	v_readlane_b32 s5, v253, 41
	v_readlane_b32 s42, v254, 48
	v_lshl_add_u64 v[22:23], s[14:15], 0, v[0:1]
	v_lshlrev_b64 v[2:3], 12, v[16:17]
	v_readlane_b32 s14, v253, 47
	v_readlane_b32 s43, v254, 49
	s_add_u32 s28, s5, s42
	v_readlane_b32 s5, v253, 42
	v_lshl_or_b32 v2, v170, 4, v2
	v_readlane_b32 s15, v253, 48
	s_addc_u32 s29, s5, s43
	v_readlane_b32 s62, v254, 17
	v_lshl_add_u64 v[24:25], s[14:15], 0, v[2:3]
	v_readlane_b32 s14, v252, 5
	v_readlane_b32 s63, v254, 18
	v_readlane_b32 s66, v254, 21
	v_readlane_b32 s67, v254, 22
	v_readlane_b32 s69, v254, 24
	v_readlane_b32 s70, v254, 25
	v_readlane_b32 s71, v254, 26
	v_readlane_b32 s72, v254, 27
	v_readlane_b32 s73, v254, 28
	v_readlane_b32 s76, v254, 31
	v_readlane_b32 s77, v254, 32
	v_readlane_b32 s78, v254, 33
	v_readlane_b32 s79, v254, 34
	v_readlane_b32 s80, v254, 35
	v_readlane_b32 s81, v254, 36
	v_readlane_b32 s82, v254, 37
	v_readlane_b32 s83, v254, 38
	v_readlane_b32 s15, v252, 6
	s_add_u32 s14, s14, s42
	v_readlane_b32 s54, v254, 9
	v_readlane_b32 s55, v254, 10
	v_readlane_b32 s65, v254, 20
	s_mov_b32 s62, 0
	s_mov_b32 s66, 0
	s_mov_b32 s72, 0
	s_mov_b32 s70, 0
	s_mov_b32 s68, 0
	s_mov_b32 s82, 0
	s_mov_b32 s80, 0
	s_mov_b32 s78, 0
	s_mov_b32 s76, 0
	v_readlane_b32 s74, v254, 52
	s_addc_u32 s15, s15, s43
	s_mov_b32 s65, 0xffff
	s_mov_b32 s63, 0x40710000
	s_mov_b32 s67, 0x406e0000
	s_mov_b32 s73, 0x40814000
	s_mov_b32 s71, 0x407fa000
	s_mov_b32 s69, 0x407ce000
	s_mov_b32 s83, 0x407a4000
	s_mov_b32 s81, 0x4077c000
	s_mov_b32 s79, 0x40756000
	s_mov_b32 s77, 0x40732000
	v_readlane_b32 s75, v254, 53
	v_cmp_eq_u32_e64 s[40:41], 0, v170
	v_lshl_add_u64 v[20:21], v[16:17], 2, s[28:29]
	v_lshlrev_b32_e32 v168, 3, v170
	v_lshl_add_u64 v[26:27], s[14:15], 0, v[0:1]
	s_mov_b64 s[54:55], 0
	v_readlane_b32 s58, v254, 13
	v_readlane_b32 s59, v254, 14
	v_readlane_b32 s60, v254, 15
	v_readlane_b32 s61, v254, 16
	v_readlane_b32 s64, v254, 19
	v_mov_b32_e32 v243, 0
	v_mov_b32_e32 v245, 0
	s_mov_b64 s[14:15], 0x4000000
	v_lshl_add_u64 v[220:221], v[22:23], 0, v[168:169]
	v_lshl_add_u64 v[222:223], v[26:27], 0, v[168:169]
	v_lshl_add_u64 v[222:223], v[222:223], 0, s[14:15]
	global_load_dwordx2 v[200:201], v[220:221], off
	global_load_dwordx2 v[202:203], v[220:221], off offset:512
	global_load_dwordx2 v[204:205], v[220:221], off offset:1024
	global_load_dwordx2 v[206:207], v[220:221], off offset:1536
	global_load_dwordx2 v[208:209], v[222:223], off
	global_load_dwordx2 v[210:211], v[222:223], off offset:512
	global_load_dwordx2 v[212:213], v[222:223], off offset:1024
	global_load_dwordx2 v[214:215], v[222:223], off offset:1536
	global_load_dword v216, v[20:21], off
	global_load_dwordx4 v[226:229], v[18:19], off
	global_load_dwordx4 v[230:233], v[18:19], off offset:1024
	global_load_dwordx4 v[234:237], v[18:19], off offset:2048
	global_load_dwordx4 v[238:241], v[18:19], off offset:3072
	s_waitcnt vmcnt(0)
	s_branch .LBB0_53

.LBB0_53:
	v_lshl_add_u64 v[28:29], v[26:27], 0, v[168:169]
	s_waitcnt vmcnt(4)
	v_mov_b64_e32 v[36:37], v[200:201]
	v_mov_b64_e32 v[38:39], v[202:203]
	v_mov_b64_e32 v[40:41], v[204:205]
	v_mov_b64_e32 v[42:43], v[206:207]
	v_mov_b64_e32 v[44:45], v[208:209]
	v_mov_b64_e32 v[46:47], v[210:211]
	v_mov_b64_e32 v[48:49], v[212:213]
	v_mov_b64_e32 v[50:51], v[214:215]
	v_mov_b32_e32 v52, v216
	v_sub_u32_e32 v218, 0x13fff, v16
	v_min_i32_e32 v218, s96, v218
	s_mov_b64 s[14:15], 0x4000000
	v_lshlrev_b32_e32 v242, 11, v218
	v_lshlrev_b32_e32 v244, 2, v218
	v_lshl_add_u64 v[220:221], v[242:243], 0, v[22:23]
	v_lshl_add_u64 v[222:223], v[242:243], 0, v[28:29]
	v_lshl_add_u64 v[224:225], v[244:245], 0, v[20:21]
	v_lshl_add_u64 v[220:221], v[220:221], 0, v[168:169]
	v_lshl_add_u64 v[222:223], v[222:223], 0, s[14:15]
	global_load_dwordx2 v[200:201], v[220:221], off
	global_load_dwordx2 v[202:203], v[220:221], off offset:512
	global_load_dwordx2 v[204:205], v[220:221], off offset:1024
	global_load_dwordx2 v[206:207], v[220:221], off offset:1536
	global_load_dwordx2 v[208:209], v[222:223], off
	global_load_dwordx2 v[210:211], v[222:223], off offset:512
	global_load_dwordx2 v[212:213], v[222:223], off offset:1024
	global_load_dwordx2 v[214:215], v[222:223], off offset:1536
	global_load_dword v216, v[224:225], off
	v_lshlrev_b32_e32 v56, 16, v36
	v_and_b32_e32 v57, 0xffff0000, v36
	v_lshlrev_b32_e32 v54, 16, v37
	v_and_b32_e32 v55, 0xffff0000, v37
	v_pk_mul_f32 v[64:65], v[56:57], v[56:57]
	v_lshlrev_b32_e32 v36, 16, v39
	v_and_b32_e32 v37, 0xffff0000, v39
	v_lshlrev_b32_e32 v58, 16, v38
	v_and_b32_e32 v59, 0xffff0000, v38
	v_lshlrev_b32_e32 v38, 16, v41
	v_and_b32_e32 v39, 0xffff0000, v41
	v_lshlrev_b32_e32 v60, 16, v40
	v_and_b32_e32 v61, 0xffff0000, v40
	v_lshlrev_b32_e32 v40, 16, v43
	v_and_b32_e32 v41, 0xffff0000, v43
	v_lshlrev_b32_e32 v62, 16, v42
	v_and_b32_e32 v63, 0xffff0000, v42
	v_pk_mul_f32 v[42:43], v[54:55], v[54:55]
	v_add_f32_e32 v17, v64, v65
	v_add_f32_e32 v17, v42, v17
	v_pk_mul_f32 v[68:69], v[58:59], v[58:59]
	v_add_f32_e32 v17, v43, v17
	v_add_f32_e32 v17, v68, v17
	v_pk_mul_f32 v[66:67], v[36:37], v[36:37]
	v_add_f32_e32 v17, v69, v17
	v_add_f32_e32 v17, v66, v17
	v_pk_mul_f32 v[72:73], v[60:61], v[60:61]
	v_add_f32_e32 v17, v67, v17
	v_add_f32_e32 v17, v72, v17
	v_pk_mul_f32 v[70:71], v[38:39], v[38:39]
	v_add_f32_e32 v17, v73, v17
	v_add_f32_e32 v17, v70, v17
	v_pk_mul_f32 v[76:77], v[62:63], v[62:63]
	v_add_f32_e32 v17, v71, v17
	v_add_f32_e32 v17, v76, v17
	v_pk_mul_f32 v[74:75], v[40:41], v[40:41]
	v_add_f32_e32 v17, v77, v17
	v_add_f32_e32 v17, v74, v17
	v_add_f32_e32 v17, v75, v17
	ds_bpermute_b32 v42, v30, v17
	s_andn2_b64 vcc, exec, s[52:53]
	s_waitcnt lgkmcnt(0)
	v_add_f32_e32 v17, v17, v42
	ds_bpermute_b32 v42, v31, v17
	s_waitcnt lgkmcnt(0)
	v_add_f32_e32 v17, v17, v42
	ds_bpermute_b32 v43, v32, v17
	s_waitcnt lgkmcnt(0)
	v_add_f32_e32 v17, v17, v43
	ds_bpermute_b32 v53, v33, v17
	s_waitcnt lgkmcnt(0)
	v_add_f32_e32 v17, v17, v53
	ds_bpermute_b32 v53, v34, v17
	s_waitcnt lgkmcnt(0)
	v_add_f32_e32 v17, v17, v53
	ds_bpermute_b32 v53, v35, v17
	v_lshlrev_b32_e32 v42, 16, v45
	v_and_b32_e32 v43, 0xffff0000, v45
	s_waitcnt lgkmcnt(0)
	v_add_f32_e32 v17, v17, v53
	v_fmamk_f32 v17, v17, 0x3a800000, v172
	v_lshlrev_b32_e32 v64, 16, v44
	v_and_b32_e32 v65, 0xffff0000, v44
	v_lshlrev_b32_e32 v44, 16, v47
	v_and_b32_e32 v45, 0xffff0000, v47
	v_lshlrev_b32_e32 v66, 16, v46
	v_and_b32_e32 v67, 0xffff0000, v46
	v_lshlrev_b32_e32 v46, 16, v49
	v_and_b32_e32 v47, 0xffff0000, v49
	v_mul_f32_e32 v49, 0x4b800000, v17
	v_cmp_gt_f32_e64 s[42:43], s4, v17
	v_lshlrev_b32_e32 v70, 16, v50
	v_and_b32_e32 v71, 0xffff0000, v50
	v_cndmask_b32_e64 v17, v17, v49, s[42:43]
	v_rsq_f32_e32 v17, v17
	v_lshlrev_b32_e32 v68, 16, v48
	v_and_b32_e32 v69, 0xffff0000, v48
	v_lshlrev_b32_e32 v48, 16, v51
	v_mul_f32_e32 v50, 0x45800000, v17
	v_cndmask_b32_e64 v50, v17, v50, s[42:43]
	v_pk_mul_f32 v[56:57], v[50:51], v[56:57] op_sel_hi:[0,1]
	v_pk_mul_f32 v[54:55], v[50:51], v[54:55] op_sel_hi:[0,1]
	v_pk_mul_f32 v[58:59], v[50:51], v[58:59] op_sel_hi:[0,1]
	v_pk_mul_f32 v[36:37], v[50:51], v[36:37] op_sel_hi:[0,1]
	v_pk_mul_f32 v[60:61], v[50:51], v[60:61] op_sel_hi:[0,1]
	v_pk_mul_f32 v[38:39], v[50:51], v[38:39] op_sel_hi:[0,1]
	v_pk_mul_f32 v[62:63], v[50:51], v[62:63] op_sel_hi:[0,1]
	v_pk_mul_f32 v[40:41], v[50:51], v[40:41] op_sel_hi:[0,1]
	v_and_b32_e32 v49, 0xffff0000, v51
	v_pk_mul_f32 v[0:1], v[226:227], v[56:57]
	v_pk_mul_f32 v[2:3], v[228:229], v[54:55]
	v_pk_mul_f32 v[4:5], v[230:231], v[58:59]
	v_pk_mul_f32 v[6:7], v[232:233], v[36:37]
	v_pk_mul_f32 v[36:37], v[234:235], v[60:61]
	v_pk_mul_f32 v[38:39], v[236:237], v[38:39]
	v_pk_mul_f32 v[50:51], v[238:239], v[62:63]
	v_pk_mul_f32 v[40:41], v[240:241], v[40:41]
	v_pk_fma_f32 v[12:13], v[52:53], v[64:65], v[0:1] op_sel_hi:[0,1,1]
	v_pk_fma_f32 v[14:15], v[52:53], v[42:43], v[2:3] op_sel_hi:[0,1,1]
	v_pk_fma_f32 v[8:9], v[52:53], v[66:67], v[4:5] op_sel_hi:[0,1,1]
	v_pk_fma_f32 v[10:11], v[52:53], v[44:45], v[6:7] op_sel_hi:[0,1,1]
	v_pk_fma_f32 v[4:5], v[52:53], v[68:69], v[36:37] op_sel_hi:[0,1,1]
	v_pk_fma_f32 v[6:7], v[52:53], v[46:47], v[38:39] op_sel_hi:[0,1,1]
	v_pk_fma_f32 v[0:1], v[52:53], v[70:71], v[50:51] op_sel_hi:[0,1,1]
	v_pk_fma_f32 v[2:3], v[52:53], v[48:49], v[40:41] op_sel_hi:[0,1,1]
	s_cbranch_vccnz .LBB0_55
	global_store_dwordx4 v[24:25], v[12:15], off offset:-2048
	global_store_dwordx4 v[24:25], v[8:11], off offset:-1024
	global_store_dwordx4 v[24:25], v[4:7], off
	global_store_dwordx4 v[24:25], v[0:3], off offset:1024

.LBB0_199:
	v_add_u32_e32 v166, s16, v198
	v_add_u32_e32 v167, 0x8000, v166
	v_add_u32_e32 v68, 0x4000, v166
	global_load_dwordx4 v[64:67], v167, s[54:55]
	s_add_i32 s17, s17, 2
	global_load_dwordx4 v[68:71], v68, s[56:57]
	ds_read_b128 v[72:75], v201 offset:8192
	ds_read_b128 v[76:79], v201 offset:12288
	ds_read_b128 v[208:211], v206 offset:8192
	ds_read_b128 v[212:215], v206 offset:12288
	s_waitcnt lgkmcnt(3)
	v_mfma_f32_32x32x16_bf16 v[96:111], v[72:75], v[120:123], v[32:47]
	v_cvt_pk_bf16_f32 v144, v48, v49
	v_add_f32_e32 v48, v48, v49
	v_add_f32_e32 v49, v50, v51
	v_add_f32_e32 v48, v48, v49
	v_cvt_pk_bf16_f32 v145, v50, v51
	v_add_f32_e32 v48, 0, v48
	s_waitcnt lgkmcnt(2)
	v_mfma_f32_32x32x16_bf16 v[80:95], v[76:79], v[120:123], v[32:47]
	v_add_f32_e32 v49, v52, v53
	v_add_f32_e32 v50, v54, v55
	v_add_f32_e32 v49, v49, v50
	v_cvt_pk_bf16_f32 v146, v52, v53
	v_cvt_pk_bf16_f32 v147, v54, v55
	v_add_f32_e32 v152, v49, v48
	ds_read_b128 v[48:51], v203 offset:8192
	ds_read_b128 v[52:55], v203 offset:12288
	ds_read_b128 v[72:75], v205 offset:8192
	ds_read_b128 v[76:79], v205 offset:12288
	s_waitcnt lgkmcnt(5)
	v_mfma_f32_32x32x16_bf16 v[96:111], v[208:211], v[116:119], v[96:111]
	v_cvt_pk_bf16_f32 v148, v56, v57
	v_add_f32_e32 v56, v56, v57
	v_add_f32_e32 v57, v58, v59
	v_add_f32_e32 v56, v56, v57
	v_cvt_pk_bf16_f32 v149, v58, v59
	v_add_f32_e32 v56, v56, v152
	s_waitcnt lgkmcnt(4)
	v_mfma_f32_32x32x16_bf16 v[80:95], v[212:215], v[116:119], v[80:95]
	v_add_f32_e32 v57, v60, v61
	v_add_f32_e32 v58, v62, v63
	v_add_f32_e32 v57, v57, v58
	v_cvt_pk_bf16_f32 v150, v60, v61
	v_cvt_pk_bf16_f32 v151, v62, v63
	v_add_f32_e32 v56, v57, v56
	s_waitcnt lgkmcnt(3)
	v_mfma_f32_32x32x16_bf16 v[96:111], v[48:51], v[112:115], v[96:111]
	v_add_f32_e64 v48, v164, v162
	v_add_f32_e64 v49, v165, v163
	v_cvt_pk_bf16_f32 v152, v162, v164
	v_add_f32_e32 v48, v48, v49
	v_cvt_pk_bf16_f32 v153, v165, v163
	v_add_f32_e32 v50, v48, v56
	s_waitcnt lgkmcnt(2)
	v_mfma_f32_32x32x16_bf16 v[80:95], v[52:55], v[112:115], v[80:95]
	v_add_f32_e64 v48, v160, v156
	v_add_f32_e64 v49, v161, v157
	v_cvt_pk_bf16_f32 v154, v156, v160
	v_add_f32_e32 v48, v48, v49
	v_cvt_pk_bf16_f32 v155, v161, v157
	v_add_f32_e32 v50, v48, v50
	s_waitcnt lgkmcnt(1)
	v_mfma_f32_32x32x16_bf16 v[96:111], v[72:75], v[124:127], v[96:111]
	v_add_f32_e64 v48, v140, v136
	v_add_f32_e64 v49, v141, v137
	v_cvt_pk_bf16_f32 v156, v136, v140
	v_add_f32_e32 v48, v48, v49
	v_cvt_pk_bf16_f32 v157, v141, v137
	v_add_f32_e32 v50, v48, v50
	s_waitcnt lgkmcnt(0)
	v_mfma_f32_32x32x16_bf16 v[80:95], v[76:79], v[124:127], v[80:95]
	v_add_f32_e64 v48, v132, v128
	v_add_f32_e64 v49, v133, v129
	v_cvt_pk_bf16_f32 v158, v128, v132
	v_add_f32_e32 v48, v48, v49
	v_cvt_pk_bf16_f32 v159, v133, v129
	v_add_f32_e32 v180, v48, v50
	ds_read_b64_tr_b16 v[48:49], v207 offset:16384
	ds_read_b64_tr_b16 v[50:51], v207 offset:16896
	ds_read_b64_tr_b16 v[52:53], v207 offset:17408
	ds_read_b64_tr_b16 v[54:55], v207 offset:17920
	ds_read_b64_tr_b16 v[56:57], v207 offset:20480
	ds_read_b64_tr_b16 v[58:59], v207 offset:20992
	ds_read_b64_tr_b16 v[60:61], v207 offset:21504
	ds_read_b64_tr_b16 v[62:63], v207 offset:22016
	s_waitcnt lgkmcnt(6)
	v_mfma_f32_32x32x16_bf16 v[16:31], v[48:51], v[144:147], v[16:31]
	v_exp_f32_e32 v96, v96
	v_exp_f32_e32 v97, v97
	v_exp_f32_e32 v98, v98
	v_exp_f32_e32 v99, v99
	s_waitcnt lgkmcnt(2)
	v_mfma_f32_32x32x16_bf16 v[0:15], v[56:59], v[144:147], v[0:15]
	v_exp_f32_e32 v100, v100
	v_exp_f32_e32 v101, v101
	v_exp_f32_e32 v102, v102
	v_exp_f32_e32 v103, v103
	ds_read_b64_tr_b16 v[48:49], v207 offset:18432
	ds_read_b64_tr_b16 v[50:51], v207 offset:18944
	ds_read_b64_tr_b16 v[56:57], v207 offset:19456
	ds_read_b64_tr_b16 v[58:59], v207 offset:19968
	ds_read_b64_tr_b16 v[72:73], v207 offset:22528
	ds_read_b64_tr_b16 v[74:75], v207 offset:23040
	ds_read_b64_tr_b16 v[76:77], v207 offset:23552
	ds_read_b64_tr_b16 v[78:79], v207 offset:24064
	v_mfma_f32_32x32x16_bf16 v[16:31], v[52:55], v[148:151], v[16:31]
	v_exp_f32_e32 v104, v104
	v_exp_f32_e32 v105, v105
	v_exp_f32_e32 v106, v106
	v_exp_f32_e32 v107, v107
	s_waitcnt lgkmcnt(8)
	v_mfma_f32_32x32x16_bf16 v[0:15], v[60:63], v[148:151], v[0:15]
	v_exp_f32_e32 v108, v108
	v_exp_f32_e32 v109, v109
	v_exp_f32_e32 v110, v110
	v_exp_f32_e32 v111, v111
	s_waitcnt lgkmcnt(6)
	v_mfma_f32_32x32x16_bf16 v[16:31], v[48:51], v[152:155], v[16:31]
	v_exp_f32_e32 v80, v80
	v_exp_f32_e32 v81, v81
	v_exp_f32_e32 v82, v82
	v_exp_f32_e32 v83, v83
	s_waitcnt lgkmcnt(2)
	v_mfma_f32_32x32x16_bf16 v[0:15], v[72:75], v[152:155], v[0:15]
	v_exp_f32_e32 v84, v84
	v_exp_f32_e32 v85, v85
	v_exp_f32_e32 v86, v86
	v_exp_f32_e32 v87, v87
	v_mfma_f32_32x32x16_bf16 v[16:31], v[56:59], v[156:159], v[16:31]
	v_exp_f32_e32 v88, v88
	v_exp_f32_e32 v89, v89
	v_exp_f32_e32 v90, v90
	v_exp_f32_e32 v91, v91
	s_waitcnt lgkmcnt(0)
	v_mfma_f32_32x32x16_bf16 v[0:15], v[76:79], v[156:159], v[0:15]
	v_exp_f32_e32 v92, v92
	v_exp_f32_e32 v93, v93
	v_exp_f32_e32 v94, v94
	v_exp_f32_e32 v95, v95
	v_add_u32_e32 v48, 0xc000, v166
	s_waitcnt vmcnt(1)
	ds_write_b128 v202, v[64:67]
	s_waitcnt vmcnt(0)
	ds_write_b128 v196, v[68:71] offset:24576
	s_waitcnt lgkmcnt(0)
	s_barrier
	global_load_dwordx4 v[160:163], v48, s[54:55]
	s_nop 0
	global_load_dwordx4 v[164:167], v167, s[56:57]
	ds_read_b128 v[64:67], v201
	ds_read_b128 v[208:211], v201 offset:4096
	ds_read_b128 v[212:215], v206
	ds_read_b128 v[216:219], v206 offset:4096
	s_waitcnt lgkmcnt(3)
	v_mfma_f32_32x32x16_bf16 v[48:63], v[64:67], v[120:123], v[32:47]
	v_add_f32_e32 v64, v96, v97
	v_add_f32_e32 v65, v98, v99
	v_add_f32_e32 v64, v64, v65
	v_cvt_pk_bf16_f32 v140, v96, v97
	v_cvt_pk_bf16_f32 v141, v98, v99
	v_add_f32_e32 v96, 0, v64
	s_waitcnt lgkmcnt(2)
	v_mfma_f32_32x32x16_bf16 v[64:79], v[208:211], v[120:123], v[32:47]
	v_add_f32_e32 v97, v100, v101
	v_add_f32_e32 v98, v102, v103
	v_add_f32_e32 v97, v97, v98
	v_cvt_pk_bf16_f32 v142, v100, v101
	v_cvt_pk_bf16_f32 v143, v102, v103
	v_add_f32_e32 v128, v97, v96
	ds_read_b128 v[96:99], v203
	ds_read_b128 v[100:103], v203 offset:4096
	ds_read_b128 v[208:211], v205
	ds_read_b128 v[220:223], v205 offset:4096
	s_waitcnt lgkmcnt(5)
	v_mfma_f32_32x32x16_bf16 v[48:63], v[212:215], v[116:119], v[48:63]
	v_cvt_pk_bf16_f32 v136, v104, v105
	v_add_f32_e32 v104, v104, v105
	v_add_f32_e32 v105, v106, v107
	v_add_f32_e32 v104, v104, v105
	v_cvt_pk_bf16_f32 v137, v106, v107
	v_add_f32_e32 v104, v104, v128
	s_waitcnt lgkmcnt(4)
	v_mfma_f32_32x32x16_bf16 v[64:79], v[216:219], v[116:119], v[64:79]
	v_add_f32_e32 v105, v108, v109
	v_add_f32_e32 v106, v110, v111
	v_add_f32_e32 v105, v105, v106
	v_cvt_pk_bf16_f32 v138, v108, v109
	v_cvt_pk_bf16_f32 v139, v110, v111
	v_add_f32_e32 v104, v105, v104
	s_waitcnt lgkmcnt(3)
	v_mfma_f32_32x32x16_bf16 v[48:63], v[96:99], v[112:115], v[48:63]
	v_cvt_pk_bf16_f32 v132, v80, v81
	v_mov_b32_e32 v96, v81
	v_mov_b32_e32 v97, v82
	v_mov_b32_e32 v81, v83
	v_pk_add_f32 v[80:81], v[96:97], v[80:81]
	v_cvt_pk_bf16_f32 v133, v82, v83
	v_add_f32_e32 v80, v80, v81
	v_add_f32_e32 v82, v80, v104
	s_waitcnt lgkmcnt(2)
	v_mfma_f32_32x32x16_bf16 v[64:79], v[100:103], v[112:115], v[64:79]
	v_cvt_pk_bf16_f32 v134, v84, v85
	v_mov_b32_e32 v80, v85
	v_mov_b32_e32 v81, v86
	v_mov_b32_e32 v85, v87
	v_pk_add_f32 v[80:81], v[80:81], v[84:85]
	v_cvt_pk_bf16_f32 v135, v86, v87
	v_add_f32_e32 v80, v80, v81
	v_add_f32_e32 v82, v80, v82
	s_waitcnt lgkmcnt(1)
	v_mfma_f32_32x32x16_bf16 v[48:63], v[208:211], v[124:127], v[48:63]
	v_cvt_pk_bf16_f32 v128, v88, v89
	v_mov_b32_e32 v80, v89
	v_mov_b32_e32 v81, v90
	v_mov_b32_e32 v89, v91
	v_pk_add_f32 v[80:81], v[80:81], v[88:89]
	v_cvt_pk_bf16_f32 v129, v90, v91
	v_add_f32_e32 v80, v80, v81
	v_add_f32_e32 v82, v80, v82
	s_waitcnt lgkmcnt(0)
	v_mfma_f32_32x32x16_bf16 v[64:79], v[220:223], v[124:127], v[64:79]
	v_cvt_pk_bf16_f32 v130, v92, v93
	v_mov_b32_e32 v80, v93
	v_mov_b32_e32 v81, v94
	v_mov_b32_e32 v93, v95
	v_pk_add_f32 v[80:81], v[80:81], v[92:93]
	v_cvt_pk_bf16_f32 v131, v94, v95
	v_add_f32_e32 v80, v80, v81
	v_add_f32_e32 v104, v80, v82
	ds_read_b64_tr_b16 v[80:81], v207 offset:24576
	ds_read_b64_tr_b16 v[82:83], v207 offset:25088
	ds_read_b64_tr_b16 v[84:85], v207 offset:28672
	ds_read_b64_tr_b16 v[86:87], v207 offset:29184
	ds_read_b64_tr_b16 v[88:89], v207 offset:25600
	ds_read_b64_tr_b16 v[90:91], v207 offset:26112
	ds_read_b64_tr_b16 v[92:93], v207 offset:29696
	ds_read_b64_tr_b16 v[94:95], v207 offset:30208
	v_add_f32_e32 v105, v197, v180
	s_waitcnt lgkmcnt(6)
	v_mfma_f32_32x32x16_bf16 v[16:31], v[80:83], v[140:143], v[16:31]
	v_exp_f32_e32 v48, v48
	v_exp_f32_e32 v49, v49
	v_exp_f32_e32 v50, v50
	v_exp_f32_e32 v51, v51
	s_waitcnt lgkmcnt(4)
	v_mfma_f32_32x32x16_bf16 v[0:15], v[84:87], v[140:143], v[0:15]
	v_exp_f32_e32 v52, v52
	v_exp_f32_e32 v53, v53
	v_exp_f32_e32 v54, v54
	v_exp_f32_e32 v55, v55
	ds_read_b64_tr_b16 v[80:81], v207 offset:26624
	ds_read_b64_tr_b16 v[82:83], v207 offset:27136
	ds_read_b64_tr_b16 v[84:85], v207 offset:27648
	ds_read_b64_tr_b16 v[86:87], v207 offset:28160
	ds_read_b64_tr_b16 v[96:97], v207 offset:30720
	ds_read_b64_tr_b16 v[98:99], v207 offset:31232
	ds_read_b64_tr_b16 v[100:101], v207 offset:31744
	ds_read_b64_tr_b16 v[102:103], v207 offset:32256
	s_waitcnt lgkmcnt(10)
	v_mfma_f32_32x32x16_bf16 v[16:31], v[88:91], v[136:139], v[16:31]
	v_exp_f32_e32 v56, v56
	v_exp_f32_e32 v57, v57
	v_exp_f32_e32 v58, v58
	v_exp_f32_e32 v59, v59
	s_waitcnt lgkmcnt(8)
	v_mfma_f32_32x32x16_bf16 v[0:15], v[92:95], v[136:139], v[0:15]
	v_exp_f32_e32 v60, v60
	v_exp_f32_e32 v61, v61
	v_exp_f32_e32 v62, v62
	v_exp_f32_e32 v63, v63
	s_waitcnt lgkmcnt(6)
	v_mfma_f32_32x32x16_bf16 v[16:31], v[80:83], v[132:135], v[16:31]
	v_exp_f32_e32 v64, v64
	v_exp_f32_e32 v65, v65
	v_exp_f32_e32 v66, v66
	v_exp_f32_e32 v67, v67
	s_waitcnt lgkmcnt(2)
	v_mfma_f32_32x32x16_bf16 v[0:15], v[96:99], v[132:135], v[0:15]
	v_exp_f32_e32 v68, v68
	v_exp_f32_e32 v69, v69
	v_exp_f32_e32 v70, v70
	v_exp_f32_e32 v71, v71
	v_mfma_f32_32x32x16_bf16 v[16:31], v[84:87], v[128:131], v[16:31]
	v_exp_f32_e32 v72, v72
	v_exp_f32_e32 v73, v73
	v_exp_f32_e32 v74, v74
	v_exp_f32_e32 v75, v75
	s_waitcnt lgkmcnt(0)
	v_mfma_f32_32x32x16_bf16 v[0:15], v[100:103], v[128:131], v[0:15]
	v_exp_f32_e32 v76, v76
	v_exp_f32_e32 v77, v77
	v_exp_f32_e32 v78, v78
	v_exp_f32_e32 v79, v79
	s_add_i32 s16, s16, 0x8000
	v_add_f32_e32 v197, v105, v104
	s_waitcnt vmcnt(1)
	ds_write_b128 v202, v[160:163] offset:8192
	s_waitcnt vmcnt(0)
	ds_write_b128 v196, v[164:167] offset:16384
	s_cmp_lt_u32 s17, s15
	v_mov_b32_e32 v162, v64
	v_mov_b32_e32 v164, v65
	v_mov_b32_e32 v165, v66
	v_mov_b32_e32 v163, v67
	v_mov_b32_e32 v156, v68
	v_mov_b32_e32 v160, v69
	v_mov_b32_e32 v161, v70
	v_mov_b32_e32 v157, v71
	v_mov_b32_e32 v136, v72
	v_mov_b32_e32 v140, v73
	v_mov_b32_e32 v141, v74
	v_mov_b32_e32 v137, v75
	v_mov_b32_e32 v128, v76
	v_mov_b32_e32 v132, v77
	v_mov_b32_e32 v133, v78
	v_mov_b32_e32 v129, v79
	s_waitcnt lgkmcnt(0)
	s_barrier
	s_cbranch_scc1 .LBB0_199
	v_add_u32_e32 v80, s16, v204
	global_load_dwordx4 v[96:99], v80, s[56:57]
	ds_read_b128 v[100:103], v201 offset:8192
	ds_read_b128 v[104:107], v201 offset:12288
	ds_read_b128 v[108:111], v206 offset:8192
	ds_read_b128 v[128:131], v206 offset:12288
	s_setprio 1
	s_waitcnt lgkmcnt(3)
	v_mfma_f32_32x32x16_bf16 v[80:95], v[100:103], v[120:123], v[32:47]
	s_setprio 0
	v_cvt_pk_bf16_f32 v100, v48, v49
	v_add_f32_e32 v48, v48, v49
	v_add_f32_e32 v49, v50, v51
	v_add_f32_e32 v48, v48, v49
	v_cvt_pk_bf16_f32 v101, v50, v51
	v_add_f32_e32 v48, 0, v48
	s_setprio 1
	s_waitcnt lgkmcnt(2)
	v_mfma_f32_32x32x16_bf16 v[32:47], v[104:107], v[120:123], v[32:47]
	s_setprio 0
	v_add_f32_e32 v49, v52, v53
	v_add_f32_e32 v50, v54, v55
	v_add_f32_e32 v49, v49, v50
	v_cvt_pk_bf16_f32 v102, v52, v53
	v_cvt_pk_bf16_f32 v103, v54, v55
	v_add_f32_e32 v132, v49, v48
	ds_read_b128 v[48:51], v203 offset:8192
	ds_read_b128 v[52:55], v203 offset:12288
	ds_read_b128 v[104:107], v205 offset:8192
	ds_read_b128 v[120:123], v205 offset:12288
	s_setprio 1
	s_waitcnt lgkmcnt(5)
	v_mfma_f32_32x32x16_bf16 v[80:95], v[108:111], v[116:119], v[80:95]
	s_setprio 0
	v_cvt_pk_bf16_f32 v108, v56, v57
	v_add_f32_e32 v56, v56, v57
	v_add_f32_e32 v57, v58, v59
	v_add_f32_e32 v56, v56, v57
	v_cvt_pk_bf16_f32 v109, v58, v59
	v_add_f32_e32 v56, v56, v132
	s_setprio 1
	s_waitcnt lgkmcnt(4)
	v_mfma_f32_32x32x16_bf16 v[32:47], v[128:131], v[116:119], v[32:47]
	s_setprio 0
	v_add_f32_e32 v57, v60, v61
	v_add_f32_e32 v58, v62, v63
	v_add_f32_e32 v57, v57, v58
	v_cvt_pk_bf16_f32 v110, v60, v61
	v_cvt_pk_bf16_f32 v111, v62, v63
	v_add_f32_e32 v56, v57, v56
	s_setprio 1
	s_waitcnt lgkmcnt(3)
	v_mfma_f32_32x32x16_bf16 v[80:95], v[48:51], v[112:115], v[80:95]
	s_setprio 0
	v_add_f32_e32 v50, v64, v65
	v_add_f32_e32 v51, v66, v67
	v_add_f32_e32 v50, v50, v51
	v_cvt_pk_bf16_f32 v48, v64, v65
	v_cvt_pk_bf16_f32 v49, v66, v67
	v_add_f32_e32 v56, v50, v56
	s_setprio 1
	s_waitcnt lgkmcnt(2)
	v_mfma_f32_32x32x16_bf16 v[32:47], v[52:55], v[112:115], v[32:47]
	s_setprio 0
	v_add_f32_e32 v52, v68, v69
	v_add_f32_e32 v53, v70, v71
	v_add_f32_e32 v52, v52, v53
	v_cvt_pk_bf16_f32 v50, v68, v69
	v_cvt_pk_bf16_f32 v51, v70, v71
	v_add_f32_e32 v56, v52, v56
	s_setprio 1
	s_waitcnt lgkmcnt(1)
	v_mfma_f32_32x32x16_bf16 v[80:95], v[104:107], v[124:127], v[80:95]
	s_setprio 0
	v_cvt_pk_bf16_f32 v52, v72, v73
	v_mov_b32_e32 v54, v73
	v_mov_b32_e32 v55, v74
	v_mov_b32_e32 v73, v75
	v_pk_add_f32 v[54:55], v[54:55], v[72:73]
	v_cvt_pk_bf16_f32 v53, v74, v75
	v_add_f32_e32 v54, v54, v55
	v_add_f32_e32 v58, v54, v56
	s_setprio 1
	s_waitcnt lgkmcnt(0)
	v_mfma_f32_32x32x16_bf16 v[32:47], v[120:123], v[124:127], v[32:47]
	s_setprio 0
	v_cvt_pk_bf16_f32 v54, v76, v77
	v_mov_b32_e32 v56, v77
	v_mov_b32_e32 v57, v78
	v_mov_b32_e32 v77, v79
	v_pk_add_f32 v[56:57], v[56:57], v[76:77]
	v_cvt_pk_bf16_f32 v55, v78, v79
	v_add_f32_e32 v56, v56, v57
	v_add_f32_e32 v104, v56, v58
	v_lshlrev_b32_e32 v56, 8, v193
	v_or3_b32 v105, v56, v200, v199
	ds_read_b64_tr_b16 v[56:57], v105 offset:16384
	ds_read_b64_tr_b16 v[58:59], v105 offset:16896
	ds_read_b64_tr_b16 v[60:61], v105 offset:17408
	ds_read_b64_tr_b16 v[62:63], v105 offset:17920
	ds_read_b64_tr_b16 v[64:65], v105 offset:20480
	ds_read_b64_tr_b16 v[66:67], v105 offset:20992
	ds_read_b64_tr_b16 v[68:69], v105 offset:21504
	ds_read_b64_tr_b16 v[70:71], v105 offset:22016
	s_setprio 1
	s_waitcnt lgkmcnt(6)
	v_mfma_f32_32x32x16_bf16 v[16:31], v[56:59], v[100:103], v[16:31]
	s_setprio 0
	v_exp_f32_e32 v80, v80
	v_exp_f32_e32 v81, v81
	v_exp_f32_e32 v82, v82
	v_exp_f32_e32 v83, v83
	s_setprio 1
	s_waitcnt lgkmcnt(2)
	v_mfma_f32_32x32x16_bf16 v[0:15], v[64:67], v[100:103], v[0:15]
	s_setprio 0
	v_exp_f32_e32 v84, v84
	v_exp_f32_e32 v85, v85
	v_exp_f32_e32 v86, v86
	v_exp_f32_e32 v87, v87
	ds_read_b64_tr_b16 v[56:57], v105 offset:18432
	ds_read_b64_tr_b16 v[58:59], v105 offset:18944
	ds_read_b64_tr_b16 v[64:65], v105 offset:19456
	ds_read_b64_tr_b16 v[66:67], v105 offset:19968
	ds_read_b64_tr_b16 v[72:73], v105 offset:22528
	ds_read_b64_tr_b16 v[74:75], v105 offset:23040
	ds_read_b64_tr_b16 v[76:77], v105 offset:23552
	ds_read_b64_tr_b16 v[78:79], v105 offset:24064
	s_setprio 1
	v_mfma_f32_32x32x16_bf16 v[16:31], v[60:63], v[108:111], v[16:31]
	s_setprio 0
	v_exp_f32_e32 v88, v88
	v_exp_f32_e32 v89, v89
	v_exp_f32_e32 v90, v90
	v_exp_f32_e32 v91, v91
	s_setprio 1
	s_waitcnt lgkmcnt(8)
	v_mfma_f32_32x32x16_bf16 v[0:15], v[68:71], v[108:111], v[0:15]
	s_setprio 0
	v_exp_f32_e32 v92, v92
	v_exp_f32_e32 v93, v93
	v_exp_f32_e32 v94, v94
	v_exp_f32_e32 v95, v95
	s_setprio 1
	s_waitcnt lgkmcnt(6)
	v_mfma_f32_32x32x16_bf16 v[16:31], v[56:59], v[48:51], v[16:31]
	s_setprio 0
	v_exp_f32_e32 v32, v32
	v_exp_f32_e32 v33, v33
	v_exp_f32_e32 v34, v34
	v_exp_f32_e32 v35, v35
	s_setprio 1
	s_waitcnt lgkmcnt(2)
	v_mfma_f32_32x32x16_bf16 v[0:15], v[72:75], v[48:51], v[0:15]
	s_setprio 0
	v_exp_f32_e32 v36, v36
	v_exp_f32_e32 v37, v37
	v_exp_f32_e32 v38, v38
	v_exp_f32_e32 v39, v39
	s_setprio 1
	v_mfma_f32_32x32x16_bf16 v[16:31], v[64:67], v[52:55], v[16:31]
	s_setprio 0
	v_exp_f32_e32 v40, v40
	v_exp_f32_e32 v41, v41
	v_exp_f32_e32 v42, v42
	v_exp_f32_e32 v43, v43
	s_setprio 1
	s_waitcnt lgkmcnt(0)
	v_mfma_f32_32x32x16_bf16 v[0:15], v[76:79], v[52:55], v[0:15]
	s_setprio 0
	v_exp_f32_e32 v44, v44
	v_exp_f32_e32 v45, v45
	v_exp_f32_e32 v46, v46
	v_exp_f32_e32 v47, v47
	s_waitcnt vmcnt(0)
	ds_write_b128 v196, v[96:99] offset:24576
	s_waitcnt lgkmcnt(0)
	s_barrier
	v_add_f32_e32 v50, v80, v81
	v_add_f32_e32 v51, v82, v83
	v_add_f32_e32 v50, v50, v51
	v_cvt_pk_bf16_f32 v48, v80, v81
	v_cvt_pk_bf16_f32 v49, v82, v83
	v_add_f32_e32 v52, 0, v50
	v_add_f32_e32 v53, v84, v85
	v_add_f32_e32 v54, v86, v87
	v_add_f32_e32 v53, v53, v54
	v_cvt_pk_bf16_f32 v50, v84, v85
	v_cvt_pk_bf16_f32 v51, v86, v87
	v_add_f32_e32 v54, v53, v52
	v_add_f32_e32 v55, v88, v89
	v_add_f32_e32 v56, v90, v91
	v_add_f32_e32 v55, v55, v56
	v_cvt_pk_bf16_f32 v52, v88, v89
	v_cvt_pk_bf16_f32 v53, v90, v91
	v_add_f32_e32 v56, v55, v54
	v_add_f32_e32 v57, v92, v93
	v_add_f32_e32 v58, v94, v95
	v_add_f32_e32 v57, v57, v58
	v_cvt_pk_bf16_f32 v54, v92, v93
	v_cvt_pk_bf16_f32 v55, v94, v95
	v_add_f32_e32 v58, v57, v56
	v_cvt_pk_bf16_f32 v56, v32, v33
	v_add_f32_e32 v32, v32, v33
	v_add_f32_e32 v33, v34, v35
	v_add_f32_e32 v32, v32, v33
	v_cvt_pk_bf16_f32 v57, v34, v35
	v_add_f32_e32 v34, v32, v58
	s_nop 0
	v_cvt_pk_bf16_f32 v58, v36, v37
	v_mov_b32_e32 v32, v37
	v_mov_b32_e32 v33, v38
	v_mov_b32_e32 v37, v39
	v_pk_add_f32 v[32:33], v[32:33], v[36:37]
	v_cvt_pk_bf16_f32 v59, v38, v39
	v_add_f32_e32 v32, v32, v33
	v_add_f32_e32 v36, v32, v34
	v_cvt_pk_bf16_f32 v32, v40, v41
	v_mov_b32_e32 v34, v41
	v_mov_b32_e32 v35, v42
	v_mov_b32_e32 v41, v43
	v_pk_add_f32 v[34:35], v[34:35], v[40:41]
	v_cvt_pk_bf16_f32 v33, v42, v43
	v_add_f32_e32 v34, v34, v35
	v_add_f32_e32 v38, v34, v36
	s_nop 0
	v_cvt_pk_bf16_f32 v34, v44, v45
	v_mov_b32_e32 v36, v45
	v_mov_b32_e32 v37, v46
	v_mov_b32_e32 v45, v47
	v_pk_add_f32 v[36:37], v[36:37], v[44:45]
	v_cvt_pk_bf16_f32 v35, v46, v47
	v_add_f32_e32 v36, v36, v37
	v_add_f32_e32 v68, v36, v38
	ds_read_b64_tr_b16 v[36:37], v105 offset:24576
	ds_read_b64_tr_b16 v[38:39], v105 offset:25088
	ds_read_b64_tr_b16 v[40:41], v105 offset:25600
	ds_read_b64_tr_b16 v[42:43], v105 offset:26112
	ds_read_b64_tr_b16 v[44:45], v105 offset:28672
	ds_read_b64_tr_b16 v[46:47], v105 offset:29184
	ds_read_b64_tr_b16 v[60:61], v105 offset:29696
	ds_read_b64_tr_b16 v[62:63], v105 offset:30208
	s_setprio 1
	s_waitcnt lgkmcnt(6)
	v_mfma_f32_32x32x16_bf16 v[16:31], v[36:39], v[48:51], v[16:31]
	s_setprio 0
	s_setprio 1
	s_waitcnt lgkmcnt(2)
	v_mfma_f32_32x32x16_bf16 v[0:15], v[44:47], v[48:51], v[0:15]
	s_setprio 0
	ds_read_b64_tr_b16 v[36:37], v105 offset:26624
	ds_read_b64_tr_b16 v[38:39], v105 offset:27136
	ds_read_b64_tr_b16 v[44:45], v105 offset:27648
	ds_read_b64_tr_b16 v[46:47], v105 offset:28160
	ds_read_b64_tr_b16 v[48:49], v105 offset:30720
	ds_read_b64_tr_b16 v[50:51], v105 offset:31232
	ds_read_b64_tr_b16 v[64:65], v105 offset:31744
	ds_read_b64_tr_b16 v[66:67], v105 offset:32256
	s_setprio 1
	v_mfma_f32_32x32x16_bf16 v[16:31], v[40:43], v[52:55], v[16:31]
	s_setprio 0
	s_setprio 1
	s_waitcnt lgkmcnt(8)
	v_mfma_f32_32x32x16_bf16 v[0:15], v[60:63], v[52:55], v[0:15]
	s_setprio 0
	s_setprio 1
	s_waitcnt lgkmcnt(6)
	v_mfma_f32_32x32x16_bf16 v[16:31], v[36:39], v[56:59], v[16:31]
	s_setprio 0
	s_setprio 1
	s_waitcnt lgkmcnt(2)
	v_mfma_f32_32x32x16_bf16 v[0:15], v[48:51], v[56:59], v[0:15]
	s_setprio 0
	s_setprio 1
	v_mfma_f32_32x32x16_bf16 v[16:31], v[44:47], v[32:35], v[16:31]
	s_setprio 0
	s_setprio 1
	s_waitcnt lgkmcnt(0)
	v_mfma_f32_32x32x16_bf16 v[0:15], v[64:67], v[32:35], v[0:15]
	s_setprio 0
	v_add_f32_e32 v32, v197, v104
	v_add_f32_e32 v32, v32, v68
	ds_bpermute_b32 v33, v168, v32
	s_lshl_b32 s30, s5, 1
	s_waitcnt lgkmcnt(0)
	s_barrier
	v_add_f32_e32 v32, v32, v33
	v_div_scale_f32 v33, s[16:17], v32, v32, 1.0
	v_rcp_f32_e32 v34, v33
	v_div_scale_f32 v35, vcc, 1.0, v32, 1.0
	s_mov_b32 s76, 0
	v_fma_f32 v36, -v33, v34, 1.0
	v_fmac_f32_e32 v34, v36, v34
	v_mul_f32_e32 v36, v35, v34
	v_fma_f32 v37, -v33, v36, v35
	v_fmac_f32_e32 v36, v37, v34
	v_fma_f32 v33, -v33, v36, v35
	v_div_fmas_f32 v33, v33, v34, v36
	v_div_fixup_f32 v32, v33, v32, 1.0
	v_pk_mul_f32 v[26:27], v[32:33], v[26:27] op_sel_hi:[0,1]
	v_pk_mul_f32 v[10:11], v[32:33], v[10:11] op_sel_hi:[0,1]
	v_pk_mul_f32 v[28:29], v[32:33], v[28:29] op_sel_hi:[0,1]
	v_pk_mul_f32 v[12:13], v[32:33], v[12:13] op_sel_hi:[0,1]
	v_pk_mul_f32 v[30:31], v[32:33], v[30:31] op_sel_hi:[0,1]
	v_pk_mul_f32 v[14:15], v[32:33], v[14:15] op_sel_hi:[0,1]
	v_lshl_or_b32 v33, v194, 5, v195
	v_pk_mul_f32 v[0:1], v[32:33], v[0:1] op_sel_hi:[0,1]
	v_pk_mul_f32 v[16:17], v[32:33], v[16:17] op_sel_hi:[0,1]
	v_pk_mul_f32 v[2:3], v[32:33], v[2:3] op_sel_hi:[0,1]
	v_pk_mul_f32 v[44:45], v[0:1], v[0:1]
	v_pk_mul_f32 v[18:19], v[32:33], v[18:19] op_sel_hi:[0,1]
	v_pk_mul_f32 v[42:43], v[2:3], v[2:3]
	v_pk_fma_f32 v[44:45], v[16:17], v[16:17], v[44:45]
	v_pk_fma_f32 v[42:43], v[18:19], v[18:19], v[42:43]
	v_pk_mul_f32 v[4:5], v[32:33], v[4:5] op_sel_hi:[0,1]
	v_add_f32_e32 v41, v44, v45
	v_pk_mul_f32 v[20:21], v[32:33], v[20:21] op_sel_hi:[0,1]
	v_pk_mul_f32 v[48:49], v[4:5], v[4:5]
	v_add_f32_e32 v41, v41, v42
	v_pk_mul_f32 v[6:7], v[32:33], v[6:7] op_sel_hi:[0,1]
	v_pk_fma_f32 v[48:49], v[20:21], v[20:21], v[48:49]
	v_add_f32_e32 v41, v41, v43
	v_pk_mul_f32 v[22:23], v[32:33], v[22:23] op_sel_hi:[0,1]
	v_pk_mul_f32 v[46:47], v[6:7], v[6:7]
	v_add_f32_e32 v41, v41, v48
	v_pk_fma_f32 v[46:47], v[22:23], v[22:23], v[46:47]
	v_pk_mul_f32 v[8:9], v[32:33], v[8:9] op_sel_hi:[0,1]
	v_add_f32_e32 v41, v41, v49
	v_add_u32_e32 v40, s14, v33
	v_pk_mul_f32 v[24:25], v[32:33], v[24:25] op_sel_hi:[0,1]
	v_pk_mul_f32 v[32:33], v[8:9], v[8:9]
	v_add_f32_e32 v41, v41, v46
	v_pk_fma_f32 v[32:33], v[24:25], v[24:25], v[32:33]
	v_add_f32_e32 v41, v41, v47
	v_pk_mul_f32 v[34:35], v[10:11], v[10:11]
	v_add_f32_e32 v32, v41, v32
	v_pk_fma_f32 v[34:35], v[26:27], v[26:27], v[34:35]
	v_add_f32_e32 v32, v32, v33
	v_pk_mul_f32 v[36:37], v[12:13], v[12:13]
	v_add_f32_e32 v32, v32, v34
	v_pk_fma_f32 v[36:37], v[28:29], v[28:29], v[36:37]
	v_add_f32_e32 v32, v32, v35
	v_pk_mul_f32 v[38:39], v[14:15], v[14:15]
	v_add_f32_e32 v32, v32, v36
	v_pk_fma_f32 v[38:39], v[30:31], v[30:31], v[38:39]
	v_add_f32_e32 v32, v32, v37
	v_add_f32_e32 v32, v32, v38
	v_add_f32_e32 v34, v32, v39
	ds_bpermute_b32 v35, v168, v34
	v_ashrrev_i32_e32 v41, 31, v40
	v_lshlrev_b64 v[32:33], 11, v[40:41]
	v_lshl_add_u64 v[32:33], s[46:47], 0, v[32:33]
	v_lshl_add_u64 v[32:33], v[32:33], 0, s[30:31]
	s_waitcnt lgkmcnt(0)
	v_add_f32_e32 v34, v34, v35
	v_fmamk_f32 v34, v34, 0x3c800000, v172
	v_mul_f32_e32 v35, 0x4b800000, v34
	v_cmp_gt_f32_e32 vcc, s4, v34
	v_lshlrev_b32_e32 v168, 3, v193
	v_lshl_add_u64 v[32:33], v[32:33], 0, v[168:169]
	v_cndmask_b32_e32 v34, v34, v35, vcc
	v_rsq_f32_e32 v34, v34
	s_mov_b32 s78, 0
	s_mov_b32 s80, 0
	s_mov_b32 s82, 0
	v_mul_f32_e32 v35, 0x45800000, v34
	v_cndmask_b32_e32 v34, v34, v35, vcc
	v_pk_mul_f32 v[16:17], v[34:35], v[16:17] op_sel_hi:[0,1]
	v_pk_mul_f32 v[18:19], v[34:35], v[18:19] op_sel_hi:[0,1]
	v_pk_mul_f32 v[0:1], v[34:35], v[0:1] op_sel_hi:[0,1]
	v_pk_mul_f32 v[2:3], v[34:35], v[2:3] op_sel_hi:[0,1]
	v_cvt_pk_bf16_f32 v16, v16, v17
	v_cvt_pk_bf16_f32 v17, v18, v19
	v_cvt_pk_bf16_f32 v0, v0, v1
	v_cvt_pk_bf16_f32 v1, v2, v3
	global_store_dwordx2 v[32:33], v[16:17], off offset:512
	v_pk_mul_f32 v[16:17], v[34:35], v[20:21] op_sel_hi:[0,1]
	v_pk_mul_f32 v[18:19], v[34:35], v[22:23] op_sel_hi:[0,1]
	global_store_dwordx2 v[32:33], v[0:1], off offset:576
	v_pk_mul_f32 v[0:1], v[34:35], v[4:5] op_sel_hi:[0,1]
	v_pk_mul_f32 v[2:3], v[34:35], v[6:7] op_sel_hi:[0,1]
	v_cvt_pk_bf16_f32 v16, v16, v17
	v_cvt_pk_bf16_f32 v17, v18, v19
	v_cvt_pk_bf16_f32 v0, v0, v1
	v_cvt_pk_bf16_f32 v1, v2, v3
	global_store_dwordx2 v[32:33], v[16:17], off offset:528
	v_pk_mul_f32 v[16:17], v[34:35], v[24:25] op_sel_hi:[0,1]
	v_pk_mul_f32 v[18:19], v[34:35], v[26:27] op_sel_hi:[0,1]
	global_store_dwordx2 v[32:33], v[0:1], off offset:592
	v_pk_mul_f32 v[0:1], v[34:35], v[8:9] op_sel_hi:[0,1]
	v_pk_mul_f32 v[2:3], v[34:35], v[10:11] op_sel_hi:[0,1]
	v_cvt_pk_bf16_f32 v16, v16, v17
	v_cvt_pk_bf16_f32 v17, v18, v19
	v_cvt_pk_bf16_f32 v0, v0, v1
	v_cvt_pk_bf16_f32 v1, v2, v3
	global_store_dwordx2 v[32:33], v[16:17], off offset:544
	v_pk_mul_f32 v[16:17], v[34:35], v[28:29] op_sel_hi:[0,1]
	v_pk_mul_f32 v[18:19], v[34:35], v[30:31] op_sel_hi:[0,1]
	global_store_dwordx2 v[32:33], v[0:1], off offset:608
	v_pk_mul_f32 v[0:1], v[34:35], v[12:13] op_sel_hi:[0,1]
	v_pk_mul_f32 v[2:3], v[34:35], v[14:15] op_sel_hi:[0,1]
	s_mov_b32 s68, 0
	s_mov_b32 s70, 0
	s_mov_b32 s72, 0
	v_readlane_b32 s74, v254, 52
	v_cvt_pk_bf16_f32 v16, v16, v17
	v_cvt_pk_bf16_f32 v17, v18, v19
	v_cvt_pk_bf16_f32 v0, v0, v1
	v_cvt_pk_bf16_f32 v1, v2, v3
	s_mov_b32 s77, 0x40732000
	s_mov_b32 s79, 0x40756000
	s_mov_b32 s81, 0x4077c000
	s_mov_b32 s83, 0x407a4000
	s_mov_b32 s69, 0x407ce000
	s_mov_b32 s71, 0x407fa000
	s_mov_b32 s73, 0x40814000
	v_readlane_b32 s75, v254, 53
	global_store_dwordx2 v[32:33], v[16:17], off offset:560
	global_store_dwordx2 v[32:33], v[0:1], off offset:624
	s_branch .LBB0_106
